# GEMM K-loop relaxed-wait selection: common trip falls through (not-taken branch), first-trip case moved out of line
# baseline (speedup 1.0000x reference)
; #define PG8_STAGE(bufoff, gbase, voff) do { _Pragma("unroll") for (int _i = 0; _i < 2; ++_i) \
;         __builtin_amdgcn_global_load_lds((const unsigned*)((const char*)(gbase) + (voff)[_i]), (LAS unsigned*)(lds + (bufoff) + ldsw + _i * 8192), 16, 0, 0); } while (0)
; #define PG8_LDA(dst, b, h) do { _Pragma("unroll") for (int m = 0; m < 4; ++m) _Pragma("unroll") for (int k = 0; k < 2; ++k) dst[m][k] = *(const LAS bf16x8*)(lds + PG8_SA(b, h) + aoff + m * 2048 + k * 1024); } while (0)
; #define PG8_LDB(dst, b, h) do { _Pragma("unroll") for (int n = 0; n < 2; ++n) _Pragma("unroll") for (int k = 0; k < 2; ++k) dst[n][k] = *(const LAS bf16x8*)(lds + PG8_SB(b, h) + boff + n * 2048 + k * 1024); } while (0)
; #define PG8_MMA(ai, bj, At, Bt) do { __builtin_amdgcn_s_setprio(1); _Pragma("unroll") for (int m = 0; m < 4; ++m) _Pragma("unroll") for (int n = 0; n < 2; ++n) _Pragma("unroll") for (int k = 0; k < 2; ++k) \
;         acc[ai][bj][m][n] = __builtin_amdgcn_mfma_f32_16x16x32_bf16(Bt[n][k], At[m][k], acc[ai][bj][m][n], 0, 0, 0); __builtin_amdgcn_s_setprio(0); } while (0)
; #define PG8_WAIT_L(n) asm volatile("s_waitcnt lgkmcnt(" #n ")" ::: "memory")
; #define PG8_BAR __builtin_amdgcn_s_barrier()
; #define PG8_FLAG(v) do { } while (0)
; #define PG8_SCHED __builtin_amdgcn_sched_barrier(0)
; template <class Epi, class Sched, bool APERM, bool ABLK = false, bool RELAX = true>
; __device__ __forceinline__ void gemm_phase(LAS unsigned char* lds, const Gemm g, const Sched& S, const Epi& E) {
;     ...
;             const bool last = (t == nt - 2);
;             const char* a1 = cA + (size_t)(t + 1) * kstepA;
;             const char* a2 = last ? nA : cA + (size_t)(t + 2) * kstepA; const char* b2 = last ? nB : cB + (size_t)(t + 2) * kstep;
;             const char* a3 = a2 + kstepA; const char* b3 = b2 + kstep;
;             PG8_LDB(B0, 0, 0); PG8_LDB(B1, 0, 1); PG8_SCHED; PG8_LDA(At, 0, 0); PG8_STAGE(PG8_SA(1, 1), a1 + hstepA, voffA);
;             PG8_WAIT_V8R; PG8_WAIT_L(0); PG8_BAR; PG8_MMA(0, 0, At, B0); PG8_MMA(0, 1, At, B1); PG8_BAR; PG8_SCHED;
;             PG8_LDA(At, 0, 1); PG8_STAGE(PG8_SB(0, 0), b2, voffB); PG8_STAGE(PG8_SB(0, 1), b2 + hstepB, voffB); PG8_STAGE(PG8_SA(0, 0), a2, voffA);
;             PG8_WAIT_V8R; PG8_FLAG(0u); PG8_WAIT_L(0); PG8_BAR; PG8_MMA(1, 0, At, B0); PG8_MMA(1, 1, At, B1); PG8_BAR; PG8_SCHED;
.LBB0_358:
	ds_read_b128 v[130:133], v179
	ds_read_b128 v[152:155], v179 offset:1024
	ds_read_b128 v[158:161], v179 offset:2048
	ds_read_b128 v[162:165], v179 offset:3072
	ds_read_b128 v[166:169], v180
	ds_read_b128 v[170:173], v180 offset:1024
	ds_read_b128 v[174:177], v180 offset:2048
	ds_read_b128 v[184:187], v180 offset:3072
	s_add_i32 s44, s8, 2
	s_add_u32 s9, s4, 0xfffc0080
	s_addc_u32 s45, s5, -1
	s_cmp_eq_u32 s8, 12
	s_cselect_b32 s8, s41, s42
	s_cselect_b32 s71, s12, s45
	s_cselect_b32 s70, s39, s9
	s_cselect_b32 s9, s40, s43
	v_lshl_add_u64 v[220:221], s[4:5], 0, v[144:145]
	s_add_i32 m0, s91, 0xc000
	ds_read_b128 v[188:191], v181
	ds_read_b128 v[192:195], v181 offset:1024
	ds_read_b128 v[196:199], v181 offset:2048
	ds_read_b128 v[200:203], v181 offset:3072
	ds_read_b128 v[204:207], v181 offset:4096
	ds_read_b128 v[208:211], v181 offset:5120
	ds_read_b128 v[212:215], v181 offset:6144
	ds_read_b128 v[216:219], v181 offset:7168
	global_load_lds_dwordx4 v[220:221], off
	v_lshl_add_u64 v[220:221], s[4:5], 0, v[146:147]
	s_add_i32 m0, s91, 0xe000
	s_nop 0
	global_load_lds_dwordx4 v[220:221], off
	s_cmp_lg_u32 s44, 0
	s_cbranch_scc0 .Lqx0
	s_waitcnt vmcnt(8)
.Lre0:
	s_waitcnt lgkmcnt(0)
	s_barrier
	s_setprio 1
	s_waitcnt lgkmcnt(0)
	v_mfma_f32_16x16x32_bf16 v[126:129], v[130:133], v[188:191], v[126:129]
	v_mfma_f32_16x16x32_bf16 v[122:125], v[158:161], v[188:191], v[122:125]
	v_mfma_f32_16x16x32_bf16 v[118:121], v[130:133], v[196:199], v[118:121]
	v_mfma_f32_16x16x32_bf16 v[114:117], v[158:161], v[196:199], v[114:117]
	v_mfma_f32_16x16x32_bf16 v[110:113], v[130:133], v[204:207], v[110:113]
	v_mfma_f32_16x16x32_bf16 v[106:109], v[158:161], v[204:207], v[106:109]
	v_mfma_f32_16x16x32_bf16 v[102:105], v[130:133], v[212:215], v[102:105]
	v_mfma_f32_16x16x32_bf16 v[98:101], v[158:161], v[212:215], v[98:101]
	v_mfma_f32_16x16x32_bf16 v[126:129], v[152:155], v[192:195], v[126:129]
	v_mfma_f32_16x16x32_bf16 v[122:125], v[162:165], v[192:195], v[122:125]
	v_mfma_f32_16x16x32_bf16 v[118:121], v[152:155], v[200:203], v[118:121]
	v_mfma_f32_16x16x32_bf16 v[114:117], v[162:165], v[200:203], v[114:117]
	v_mfma_f32_16x16x32_bf16 v[110:113], v[152:155], v[208:211], v[110:113]
	v_mfma_f32_16x16x32_bf16 v[106:109], v[162:165], v[208:211], v[106:109]
	v_mfma_f32_16x16x32_bf16 v[102:105], v[152:155], v[216:219], v[102:105]
	v_mfma_f32_16x16x32_bf16 v[98:101], v[162:165], v[216:219], v[98:101]
	s_setprio 0
	s_setprio 1
	v_mfma_f32_16x16x32_bf16 v[62:65], v[166:169], v[188:191], v[62:65]
	v_mfma_f32_16x16x32_bf16 v[58:61], v[174:177], v[188:191], v[58:61]
	v_mfma_f32_16x16x32_bf16 v[54:57], v[166:169], v[196:199], v[54:57]
	v_mfma_f32_16x16x32_bf16 v[50:53], v[174:177], v[196:199], v[50:53]
	v_mfma_f32_16x16x32_bf16 v[46:49], v[166:169], v[204:207], v[46:49]
	v_mfma_f32_16x16x32_bf16 v[42:45], v[174:177], v[204:207], v[42:45]
	v_mfma_f32_16x16x32_bf16 v[38:41], v[166:169], v[212:215], v[38:41]
	v_mfma_f32_16x16x32_bf16 v[34:37], v[174:177], v[212:215], v[34:37]
	v_mfma_f32_16x16x32_bf16 v[62:65], v[170:173], v[192:195], v[62:65]
	v_mfma_f32_16x16x32_bf16 v[58:61], v[184:187], v[192:195], v[58:61]
	v_mfma_f32_16x16x32_bf16 v[54:57], v[170:173], v[200:203], v[54:57]
	v_mfma_f32_16x16x32_bf16 v[50:53], v[184:187], v[200:203], v[50:53]
	v_mfma_f32_16x16x32_bf16 v[46:49], v[170:173], v[208:211], v[46:49]
	v_mfma_f32_16x16x32_bf16 v[42:45], v[184:187], v[208:211], v[42:45]
	v_mfma_f32_16x16x32_bf16 v[38:41], v[170:173], v[216:219], v[38:41]
	v_mfma_f32_16x16x32_bf16 v[34:37], v[184:187], v[216:219], v[34:37]
	s_setprio 0
	s_barrier
	s_add_i32 s45, s30, s90
	v_lshl_add_u64 v[220:221], s[8:9], 0, v[136:137]
	s_mov_b32 m0, s45
	ds_read_b128 v[188:191], v181 offset:16384
	ds_read_b128 v[192:195], v181 offset:17408
	ds_read_b128 v[196:199], v181 offset:18432
	ds_read_b128 v[200:203], v181 offset:19456
	ds_read_b128 v[204:207], v181 offset:20480
	ds_read_b128 v[208:211], v181 offset:21504
	ds_read_b128 v[212:215], v181 offset:22528
	ds_read_b128 v[216:219], v181 offset:23552
	global_load_lds_dwordx4 v[220:221], off
	s_add_i32 m0, s45, 0x2000
	s_add_u32 s46, s8, 0x40000
	v_lshl_add_u64 v[222:223], s[8:9], 0, v[140:141]
	s_addc_u32 s47, s9, 0
	s_add_i32 s45, s14, s90
	global_load_lds_dwordx4 v[222:223], off
	v_lshl_add_u64 v[224:225], s[46:47], 0, v[136:137]
	s_mov_b32 m0, s45
	v_lshl_add_u64 v[226:227], s[70:71], 0, v[138:139]
	global_load_lds_dwordx4 v[224:225], off
	v_lshl_add_u64 v[224:225], s[46:47], 0, v[140:141]
	s_add_i32 m0, s45, 0x2000
	s_nop 0
	global_load_lds_dwordx4 v[224:225], off
	v_lshl_add_u64 v[224:225], s[70:71], 0, v[134:135]
	s_mov_b32 m0, s91
	s_nop 0
	global_load_lds_dwordx4 v[224:225], off
	s_mov_b32 m0, s92
	s_nop 0
	global_load_lds_dwordx4 v[226:227], off
	s_cmp_lg_u32 s44, 0
	s_cbranch_scc0 .Lqx1
	s_waitcnt vmcnt(8)

.Lqx1:
	s_cmp_eq_u32 s7, 0
	s_cbranch_scc1 .Lqy1
	s_waitcnt vmcnt(24)
	s_branch .Lre1
.Lqy1:
	s_waitcnt vmcnt(8)
	s_branch .Lre1

; #define PG8_STAGE(bufoff, gbase, voff) do { _Pragma("unroll") for (int _i = 0; _i < 2; ++_i) \
;         __builtin_amdgcn_global_load_lds((const unsigned*)((const char*)(gbase) + (voff)[_i]), (LAS unsigned*)(lds + (bufoff) + ldsw + _i * 8192), 16, 0, 0); } while (0)
; #define PG8_LDA(dst, b, h) do { _Pragma("unroll") for (int m = 0; m < 4; ++m) _Pragma("unroll") for (int k = 0; k < 2; ++k) dst[m][k] = *(const LAS bf16x8*)(lds + PG8_SA(b, h) + aoff + m * 2048 + k * 1024); } while (0)
; #define PG8_LDB(dst, b, h) do { _Pragma("unroll") for (int n = 0; n < 2; ++n) _Pragma("unroll") for (int k = 0; k < 2; ++k) dst[n][k] = *(const LAS bf16x8*)(lds + PG8_SB(b, h) + boff + n * 2048 + k * 1024); } while (0)
; #define PG8_MMA(ai, bj, At, Bt) do { __builtin_amdgcn_s_setprio(1); _Pragma("unroll") for (int m = 0; m < 4; ++m) _Pragma("unroll") for (int n = 0; n < 2; ++n) _Pragma("unroll") for (int k = 0; k < 2; ++k) \
;         acc[ai][bj][m][n] = __builtin_amdgcn_mfma_f32_16x16x32_bf16(Bt[n][k], At[m][k], acc[ai][bj][m][n], 0, 0, 0); __builtin_amdgcn_s_setprio(0); } while (0)
; #define PG8_WAIT_L(n) asm volatile("s_waitcnt lgkmcnt(" #n ")" ::: "memory")
; #define PG8_BAR __builtin_amdgcn_s_barrier()
; #define PG8_FLAG(v) do { } while (0)
; #define PG8_SCHED __builtin_amdgcn_sched_barrier(0)
; template <class Epi, class Sched, bool APERM, bool ABLK = false, bool RELAX = true>
; __device__ __forceinline__ void gemm_phase(LAS unsigned char* lds, const Gemm g, const Sched& S, const Epi& E) {
;     ...
;             const bool last = (t == nt - 2);
;             const char* a1 = cA + (size_t)(t + 1) * kstepA;
;             const char* a2 = last ? nA : cA + (size_t)(t + 2) * kstepA; const char* b2 = last ? nB : cB + (size_t)(t + 2) * kstep;
;             const char* a3 = a2 + kstepA; const char* b3 = b2 + kstep;
;             PG8_LDB(B0, 0, 0); PG8_LDB(B1, 0, 1); PG8_SCHED; PG8_LDA(At, 0, 0); PG8_STAGE(PG8_SA(1, 1), a1 + hstepA, voffA);
;             PG8_WAIT_V8R; PG8_WAIT_L(0); PG8_BAR; PG8_MMA(0, 0, At, B0); PG8_MMA(0, 1, At, B1); PG8_BAR; PG8_SCHED;
;             PG8_LDA(At, 0, 1); PG8_STAGE(PG8_SB(0, 0), b2, voffB); PG8_STAGE(PG8_SB(0, 1), b2 + hstepB, voffB); PG8_STAGE(PG8_SA(0, 0), a2, voffA);
;             PG8_WAIT_V8R; PG8_FLAG(0u); PG8_WAIT_L(0); PG8_BAR; PG8_MMA(1, 0, At, B0); PG8_MMA(1, 1, At, B1); PG8_BAR; PG8_SCHED;
.LBB0_667:
	s_lshl_b32 s70, s69, 7
	s_add_u32 s71, s54, s70
	ds_read_b128 v[146:149], v179
	ds_read_b128 v[150:153], v179 offset:1024
	ds_read_b128 v[154:157], v179 offset:2048
	ds_read_b128 v[158:161], v179 offset:3072
	ds_read_b128 v[130:133], v180
	ds_read_b128 v[134:137], v180 offset:1024
	ds_read_b128 v[138:141], v180 offset:2048
	ds_read_b128 v[142:145], v180 offset:3072
	s_addc_u32 s72, s55, 0
	s_add_u32 s73, s71, 0x100
	s_addc_u32 s74, s72, 0
	s_and_b64 s[64:65], s[62:63], exec
	s_cselect_b32 s65, s67, s74
	s_cselect_b32 s64, s68, s73
	s_add_u32 s70, s18, s70
	s_addc_u32 s73, s19, 0
	s_add_u32 s70, s70, 0x100
	s_addc_u32 s73, s73, 0
	s_and_b64 s[62:63], s[62:63], exec
	s_cselect_b32 s63, s13, s73
	s_cselect_b32 s62, s12, s70
	s_add_u32 s70, s71, 0x20080
	s_addc_u32 s71, s72, 0
	s_mov_b32 m0, s41
	v_lshl_add_u64 v[208:209], s[70:71], 0, v[176:177]
	ds_read_b128 v[184:187], v181
	ds_read_b128 v[188:191], v181 offset:1024
	ds_read_b128 v[192:195], v181 offset:2048
	ds_read_b128 v[196:199], v181 offset:3072
	ds_read_b128 v[200:203], v181 offset:4096
	ds_read_b128 v[204:207], v181 offset:5120
	ds_read_b128 v[166:169], v181 offset:6144
	ds_read_b128 v[162:165], v181 offset:7168
	global_load_lds_dwordx4 v[208:209], off
	v_lshl_add_u64 v[208:209], s[70:71], 0, v[172:173]
	s_mov_b32 m0, s42
	s_nop 0
	global_load_lds_dwordx4 v[208:209], off
	s_cmp_lg_u32 s69, 0
	s_cbranch_scc0 .Lqx2
	s_waitcnt vmcnt(8)
.Lre2:
	s_waitcnt lgkmcnt(0)
	s_barrier
	s_setprio 1
	s_setprio 0
	s_setprio 1
	s_setprio 0
	s_barrier
	s_waitcnt lgkmcnt(0)
	v_mfma_f32_16x16x32_bf16 v[126:129], v[146:149], v[184:187], v[126:129]
	s_mov_b32 m0, s43
	v_lshl_add_u64 v[224:225], s[62:63], 0, v[174:175]
	s_add_u32 s70, s62, 0x10000
	v_mfma_f32_16x16x32_bf16 v[122:125], v[154:157], v[184:187], v[122:125]
	v_lshl_add_u64 v[234:235], s[62:63], 0, v[170:171]
	s_addc_u32 s71, s63, 0
	v_lshl_add_u64 v[236:237], s[64:65], 0, v[176:177]
	v_mfma_f32_16x16x32_bf16 v[86:89], v[130:133], v[184:187], v[86:89]
	v_lshl_add_u64 v[238:239], s[64:65], 0, v[172:173]
	v_mfma_f32_16x16x32_bf16 v[78:81], v[138:141], v[184:187], v[78:81]
	v_mfma_f32_16x16x32_bf16 v[126:129], v[150:153], v[188:191], v[126:129]
	v_mfma_f32_16x16x32_bf16 v[122:125], v[158:161], v[188:191], v[122:125]
	v_mfma_f32_16x16x32_bf16 v[86:89], v[134:137], v[188:191], v[86:89]
	v_mfma_f32_16x16x32_bf16 v[78:81], v[142:145], v[188:191], v[78:81]
	ds_read_b128 v[184:187], v181 offset:16384
	ds_read_b128 v[188:191], v181 offset:17408
	ds_read_b128 v[208:211], v181 offset:18432
	ds_read_b128 v[212:215], v181 offset:19456
	ds_read_b128 v[216:219], v181 offset:20480
	ds_read_b128 v[220:223], v181 offset:21504
	ds_read_b128 v[226:229], v181 offset:22528
	ds_read_b128 v[230:233], v181 offset:23552
	global_load_lds_dwordx4 v[224:225], off
	s_mov_b32 m0, s44
	v_mfma_f32_16x16x32_bf16 v[118:121], v[146:149], v[192:195], v[118:121]
	global_load_lds_dwordx4 v[234:235], off
	s_mov_b32 m0, s45
	v_mfma_f32_16x16x32_bf16 v[114:117], v[154:157], v[192:195], v[114:117]
	v_mfma_f32_16x16x32_bf16 v[70:73], v[130:133], v[192:195], v[70:73]
	v_mfma_f32_16x16x32_bf16 v[58:61], v[138:141], v[192:195], v[58:61]
	v_lshl_add_u64 v[192:193], s[70:71], 0, v[174:175]
	global_load_lds_dwordx4 v[192:193], off
	v_lshl_add_u64 v[192:193], s[70:71], 0, v[170:171]
	s_mov_b32 m0, s46
	v_mfma_f32_16x16x32_bf16 v[110:113], v[146:149], v[200:203], v[110:113]
	global_load_lds_dwordx4 v[192:193], off
	s_mov_b32 m0, s3
	v_mfma_f32_16x16x32_bf16 v[106:109], v[154:157], v[200:203], v[106:109]
	global_load_lds_dwordx4 v[236:237], off
	s_mov_b32 m0, s34
	v_mfma_f32_16x16x32_bf16 v[102:105], v[146:149], v[166:169], v[102:105]
	global_load_lds_dwordx4 v[238:239], off
	s_cmp_lg_u32 s69, 0
	s_cbranch_scc0 .Lqx3
	s_waitcnt vmcnt(8)

.Lqx3:
	s_cmp_eq_u32 s59, 0
	s_cbranch_scc1 .Lqy3
	s_waitcnt vmcnt(24)
	s_branch .Lre3

; #define PG8_STAGE(bufoff, gbase, voff) do { _Pragma("unroll") for (int _i = 0; _i < 2; ++_i) \
;         __builtin_amdgcn_global_load_lds((const unsigned*)((const char*)(gbase) + (voff)[_i]), (LAS unsigned*)(lds + (bufoff) + ldsw + _i * 8192), 16, 0, 0); } while (0)
; #define PG8_LDA(dst, b, h) do { _Pragma("unroll") for (int m = 0; m < 4; ++m) _Pragma("unroll") for (int k = 0; k < 2; ++k) dst[m][k] = *(const LAS bf16x8*)(lds + PG8_SA(b, h) + aoff + m * 2048 + k * 1024); } while (0)
; #define PG8_LDB(dst, b, h) do { _Pragma("unroll") for (int n = 0; n < 2; ++n) _Pragma("unroll") for (int k = 0; k < 2; ++k) dst[n][k] = *(const LAS bf16x8*)(lds + PG8_SB(b, h) + boff + n * 2048 + k * 1024); } while (0)
; #define PG8_MMA(ai, bj, At, Bt) do { __builtin_amdgcn_s_setprio(1); _Pragma("unroll") for (int m = 0; m < 4; ++m) _Pragma("unroll") for (int n = 0; n < 2; ++n) _Pragma("unroll") for (int k = 0; k < 2; ++k) \
;         acc[ai][bj][m][n] = __builtin_amdgcn_mfma_f32_16x16x32_bf16(Bt[n][k], At[m][k], acc[ai][bj][m][n], 0, 0, 0); __builtin_amdgcn_s_setprio(0); } while (0)
; #define PG8_WAIT_L(n) asm volatile("s_waitcnt lgkmcnt(" #n ")" ::: "memory")
; #define PG8_BAR __builtin_amdgcn_s_barrier()
; #define PG8_FLAG(v) do { } while (0)
; #define PG8_SCHED __builtin_amdgcn_sched_barrier(0)
; template <class Epi, class Sched, bool APERM, bool ABLK = false, bool RELAX = true>
; __device__ __forceinline__ void gemm_phase(LAS unsigned char* lds, const Gemm g, const Sched& S, const Epi& E) {
;     ...
;             const bool last = (t == nt - 2);
;             const char* a1 = cA + (size_t)(t + 1) * kstepA;
;             const char* a2 = last ? nA : cA + (size_t)(t + 2) * kstepA; const char* b2 = last ? nB : cB + (size_t)(t + 2) * kstep;
;             const char* a3 = a2 + kstepA; const char* b3 = b2 + kstep;
;             PG8_LDB(B0, 0, 0); PG8_LDB(B1, 0, 1); PG8_SCHED; PG8_LDA(At, 0, 0); PG8_STAGE(PG8_SA(1, 1), a1 + hstepA, voffA);
;             PG8_WAIT_V8R; PG8_WAIT_L(0); PG8_BAR; PG8_MMA(0, 0, At, B0); PG8_MMA(0, 1, At, B1); PG8_BAR; PG8_SCHED;
;             PG8_LDA(At, 0, 1); PG8_STAGE(PG8_SB(0, 0), b2, voffB); PG8_STAGE(PG8_SB(0, 1), b2 + hstepB, voffB); PG8_STAGE(PG8_SA(0, 0), a2, voffA);
;             PG8_WAIT_V8R; PG8_FLAG(0u); PG8_WAIT_L(0); PG8_BAR; PG8_MMA(1, 0, At, B0); PG8_MMA(1, 1, At, B1); PG8_BAR; PG8_SCHED;
.LBB0_686:
	ds_read_b128 v[148:151], v159
	ds_read_b128 v[152:155], v159 offset:1024
	ds_read_b128 v[164:167], v159 offset:2048
	ds_read_b128 v[168:171], v159 offset:3072
	ds_read_b128 v[172:175], v160
	ds_read_b128 v[176:179], v160 offset:1024
	ds_read_b128 v[180:183], v160 offset:2048
	ds_read_b128 v[184:187], v160 offset:3072
	s_add_i32 s78, s68, 2
	s_add_u32 s4, s66, 0x100
	s_addc_u32 s5, s67, 0
	s_cmp_eq_u32 s68, 2
	s_cselect_b32 s68, s64, s75
	s_cselect_b32 s71, s63, s5
	s_cselect_b32 s70, s62, s4
	s_cselect_b32 s69, s65, s77
	v_lshl_add_u64 v[156:157], s[66:67], 0, v[138:139]
	s_add_i32 m0, s39, 0xc000
	ds_read_b128 v[188:191], v161
	ds_read_b128 v[192:195], v161 offset:1024
	ds_read_b128 v[196:199], v161 offset:2048
	ds_read_b128 v[200:203], v161 offset:3072
	ds_read_b128 v[204:207], v161 offset:4096
	ds_read_b128 v[208:211], v161 offset:5120
	ds_read_b128 v[212:215], v161 offset:6144
	ds_read_b128 v[216:219], v161 offset:7168
	global_load_lds_dwordx4 v[156:157], off
	v_lshl_add_u64 v[156:157], s[66:67], 0, v[140:141]
	s_add_i32 m0, s39, 0xe000
	s_nop 0
	global_load_lds_dwordx4 v[156:157], off
	s_cmp_lg_u32 s78, 0
	s_cbranch_scc0 .Lqx4
	s_waitcnt vmcnt(8)
.Lre4:
	s_waitcnt lgkmcnt(0)
	s_barrier
	s_setprio 1
	s_waitcnt lgkmcnt(0)
	v_mfma_f32_16x16x32_bf16 v[126:129], v[148:151], v[188:191], v[126:129]
	v_mfma_f32_16x16x32_bf16 v[122:125], v[164:167], v[188:191], v[122:125]
	v_mfma_f32_16x16x32_bf16 v[110:113], v[148:151], v[196:199], v[110:113]
	v_mfma_f32_16x16x32_bf16 v[106:109], v[164:167], v[196:199], v[106:109]
	v_mfma_f32_16x16x32_bf16 v[94:97], v[148:151], v[204:207], v[94:97]
	v_mfma_f32_16x16x32_bf16 v[90:93], v[164:167], v[204:207], v[90:93]
	v_mfma_f32_16x16x32_bf16 v[78:81], v[148:151], v[212:215], v[78:81]
	v_mfma_f32_16x16x32_bf16 v[74:77], v[164:167], v[212:215], v[74:77]
	v_mfma_f32_16x16x32_bf16 v[126:129], v[152:155], v[192:195], v[126:129]
	v_mfma_f32_16x16x32_bf16 v[122:125], v[168:171], v[192:195], v[122:125]
	v_mfma_f32_16x16x32_bf16 v[110:113], v[152:155], v[200:203], v[110:113]
	v_mfma_f32_16x16x32_bf16 v[106:109], v[168:171], v[200:203], v[106:109]
	v_mfma_f32_16x16x32_bf16 v[94:97], v[152:155], v[208:211], v[94:97]
	v_mfma_f32_16x16x32_bf16 v[90:93], v[168:171], v[208:211], v[90:93]
	v_mfma_f32_16x16x32_bf16 v[78:81], v[152:155], v[216:219], v[78:81]
	v_mfma_f32_16x16x32_bf16 v[74:77], v[168:171], v[216:219], v[74:77]
	s_setprio 0
	s_setprio 1
	v_mfma_f32_16x16x32_bf16 v[118:121], v[172:175], v[188:191], v[118:121]
	v_mfma_f32_16x16x32_bf16 v[114:117], v[180:183], v[188:191], v[114:117]
	v_mfma_f32_16x16x32_bf16 v[102:105], v[172:175], v[196:199], v[102:105]
	v_mfma_f32_16x16x32_bf16 v[98:101], v[180:183], v[196:199], v[98:101]
	v_mfma_f32_16x16x32_bf16 v[86:89], v[172:175], v[204:207], v[86:89]
	v_mfma_f32_16x16x32_bf16 v[82:85], v[180:183], v[204:207], v[82:85]
	v_mfma_f32_16x16x32_bf16 v[70:73], v[172:175], v[212:215], v[70:73]
	v_mfma_f32_16x16x32_bf16 v[66:69], v[180:183], v[212:215], v[66:69]
	v_mfma_f32_16x16x32_bf16 v[118:121], v[176:179], v[192:195], v[118:121]
	v_mfma_f32_16x16x32_bf16 v[114:117], v[184:187], v[192:195], v[114:117]
	v_mfma_f32_16x16x32_bf16 v[102:105], v[176:179], v[200:203], v[102:105]
	v_mfma_f32_16x16x32_bf16 v[98:101], v[184:187], v[200:203], v[98:101]
	v_mfma_f32_16x16x32_bf16 v[86:89], v[176:179], v[208:211], v[86:89]
	v_mfma_f32_16x16x32_bf16 v[82:85], v[184:187], v[208:211], v[82:85]
	v_mfma_f32_16x16x32_bf16 v[70:73], v[176:179], v[216:219], v[70:73]
	v_mfma_f32_16x16x32_bf16 v[66:69], v[184:187], v[216:219], v[66:69]
	s_setprio 0
	s_barrier
	s_add_i32 s28, s31, s38
	v_lshl_add_u64 v[156:157], s[68:69], 0, v[132:133]
	s_mov_b32 m0, s28
	ds_read_b128 v[188:191], v161 offset:16384
	ds_read_b128 v[192:195], v161 offset:17408
	ds_read_b128 v[196:199], v161 offset:18432
	ds_read_b128 v[200:203], v161 offset:19456
	ds_read_b128 v[204:207], v161 offset:20480
	ds_read_b128 v[208:211], v161 offset:21504
	ds_read_b128 v[212:215], v161 offset:22528
	ds_read_b128 v[216:219], v161 offset:23552
	global_load_lds_dwordx4 v[156:157], off
	s_add_i32 m0, s28, 0x2000
	s_add_u32 s28, s68, 0x18000
	v_lshl_add_u64 v[220:221], s[68:69], 0, v[136:137]
	s_addc_u32 s29, s69, 0
	s_add_i32 s66, s76, s38
	global_load_lds_dwordx4 v[220:221], off
	v_lshl_add_u64 v[222:223], s[28:29], 0, v[132:133]
	s_mov_b32 m0, s66
	v_lshl_add_u64 v[224:225], s[70:71], 0, v[134:135]
	global_load_lds_dwordx4 v[222:223], off
	v_lshl_add_u64 v[222:223], s[28:29], 0, v[136:137]
	s_add_i32 m0, s66, 0x2000
	s_nop 0
	global_load_lds_dwordx4 v[222:223], off
	v_lshl_add_u64 v[222:223], s[70:71], 0, v[130:131]
	s_mov_b32 m0, s39
	s_nop 0
	global_load_lds_dwordx4 v[222:223], off
	s_mov_b32 m0, s40
	s_nop 0
	global_load_lds_dwordx4 v[224:225], off
	s_cmp_lg_u32 s78, 0
	s_cbranch_scc0 .Lqx5
	s_waitcnt vmcnt(8)

; #define PG8_STAGE(bufoff, gbase, voff) do { _Pragma("unroll") for (int _i = 0; _i < 2; ++_i) \
;         __builtin_amdgcn_global_load_lds((const unsigned*)((const char*)(gbase) + (voff)[_i]), (LAS unsigned*)(lds + (bufoff) + ldsw + _i * 8192), 16, 0, 0); } while (0)
; #define PG8_LDA(dst, b, h) do { _Pragma("unroll") for (int m = 0; m < 4; ++m) _Pragma("unroll") for (int k = 0; k < 2; ++k) dst[m][k] = *(const LAS bf16x8*)(lds + PG8_SA(b, h) + aoff + m * 2048 + k * 1024); } while (0)
; #define PG8_LDB(dst, b, h) do { _Pragma("unroll") for (int n = 0; n < 2; ++n) _Pragma("unroll") for (int k = 0; k < 2; ++k) dst[n][k] = *(const LAS bf16x8*)(lds + PG8_SB(b, h) + boff + n * 2048 + k * 1024); } while (0)
; #define PG8_MMA(ai, bj, At, Bt) do { __builtin_amdgcn_s_setprio(1); _Pragma("unroll") for (int m = 0; m < 4; ++m) _Pragma("unroll") for (int n = 0; n < 2; ++n) _Pragma("unroll") for (int k = 0; k < 2; ++k) \
;         acc[ai][bj][m][n] = __builtin_amdgcn_mfma_f32_16x16x32_bf16(Bt[n][k], At[m][k], acc[ai][bj][m][n], 0, 0, 0); __builtin_amdgcn_s_setprio(0); } while (0)
; #define PG8_WAIT_L(n) asm volatile("s_waitcnt lgkmcnt(" #n ")" ::: "memory")
; #define PG8_BAR __builtin_amdgcn_s_barrier()
; #define PG8_FLAG(v) do { } while (0)
; #define PG8_SCHED __builtin_amdgcn_sched_barrier(0)
; template <class Epi, class Sched, bool APERM, bool ABLK = false, bool RELAX = true>
; __device__ __forceinline__ void gemm_phase(LAS unsigned char* lds, const Gemm g, const Sched& S, const Epi& E) {
;     ...
;             const bool last = (t == nt - 2);
;             const char* a1 = cA + (size_t)(t + 1) * kstepA;
;             const char* a2 = last ? nA : cA + (size_t)(t + 2) * kstepA; const char* b2 = last ? nB : cB + (size_t)(t + 2) * kstep;
;             const char* a3 = a2 + kstepA; const char* b3 = b2 + kstep;
;             PG8_LDB(B0, 0, 0); PG8_LDB(B1, 0, 1); PG8_SCHED; PG8_LDA(At, 0, 0); PG8_STAGE(PG8_SA(1, 1), a1 + hstepA, voffA);
;             PG8_WAIT_V8R; PG8_WAIT_L(0); PG8_BAR; PG8_MMA(0, 0, At, B0); PG8_MMA(0, 1, At, B1); PG8_BAR; PG8_SCHED;
;             PG8_LDA(At, 0, 1); PG8_STAGE(PG8_SB(0, 0), b2, voffB); PG8_STAGE(PG8_SB(0, 1), b2 + hstepB, voffB); PG8_STAGE(PG8_SA(0, 0), a2, voffA);
;             PG8_WAIT_V8R; PG8_FLAG(0u); PG8_WAIT_L(0); PG8_BAR; PG8_MMA(1, 0, At, B0); PG8_MMA(1, 1, At, B1); PG8_BAR; PG8_SCHED;
.LBB0_736:
	s_lshl_b32 s79, s78, 7
	s_add_u32 s80, s68, s79
	ds_read_b128 v[146:149], v196
	ds_read_b128 v[150:153], v196 offset:1024
	ds_read_b128 v[154:157], v196 offset:2048
	ds_read_b128 v[158:161], v196 offset:3072
	ds_read_b128 v[130:133], v197
	ds_read_b128 v[134:137], v197 offset:1024
	ds_read_b128 v[138:141], v197 offset:2048
	ds_read_b128 v[142:145], v197 offset:3072
	s_addc_u32 s81, s69, 0
	s_add_u32 s82, s80, 0x100
	s_addc_u32 s83, s81, 0
	s_and_b64 s[74:75], s[72:73], exec
	s_cselect_b32 s75, s51, s83
	s_cselect_b32 s74, s59, s82
	s_add_u32 s79, s66, s79
	s_addc_u32 s82, s67, 0
	s_add_u32 s79, s79, 0x100
	s_addc_u32 s82, s82, 0
	s_and_b64 s[72:73], s[72:73], exec
	s_cselect_b32 s73, s55, s82
	s_cselect_b32 s72, s77, s79
	s_add_u32 s80, s80, 0x10080
	s_addc_u32 s81, s81, 0
	v_lshl_add_u64 v[212:213], s[80:81], 0, v[182:183]
	s_add_i32 m0, s34, 0xc000
	ds_read_b128 v[200:203], v198
	ds_read_b128 v[204:207], v198 offset:1024
	ds_read_b128 v[208:211], v198 offset:2048
	ds_read_b128 v[178:181], v198 offset:3072
	ds_read_b128 v[174:177], v198 offset:4096
	ds_read_b128 v[170:173], v198 offset:5120
	ds_read_b128 v[166:169], v198 offset:6144
	ds_read_b128 v[162:165], v198 offset:7168
	global_load_lds_dwordx4 v[212:213], off
	v_lshl_add_u64 v[212:213], s[80:81], 0, v[186:187]
	s_add_i32 m0, s34, 0xe000
	s_nop 0
	global_load_lds_dwordx4 v[212:213], off
	s_cmp_lg_u32 s78, 0
	s_cbranch_scc0 .Lqx6
	s_waitcnt vmcnt(8)
.Lre6:
	s_waitcnt lgkmcnt(0)
	s_barrier
	s_setprio 1
	s_setprio 0
	s_setprio 1
	s_setprio 0
	s_barrier
	s_waitcnt lgkmcnt(0)
	v_mfma_f32_16x16x32_bf16 v[126:129], v[146:149], v[200:203], v[126:129]
	s_add_i32 s79, s31, s38
	v_lshl_add_u64 v[224:225], s[72:73], 0, v[184:185]
	s_mov_b32 m0, s79
	v_mfma_f32_16x16x32_bf16 v[122:125], v[154:157], v[200:203], v[122:125]
	ds_read_b128 v[212:215], v198 offset:16384
	ds_read_b128 v[216:219], v198 offset:17408
	v_lshl_add_u64 v[238:239], s[72:73], 0, v[188:189]
	v_lshl_add_u64 v[240:241], s[74:75], 0, v[182:183]
	v_mfma_f32_16x16x32_bf16 v[118:121], v[130:133], v[200:203], v[118:121]
	v_lshl_add_u64 v[242:243], s[74:75], 0, v[186:187]
	v_mfma_f32_16x16x32_bf16 v[114:117], v[138:141], v[200:203], v[114:117]
	ds_read_b128 v[200:203], v198 offset:18432
	ds_read_b128 v[220:223], v198 offset:19456
	ds_read_b128 v[226:229], v198 offset:20480
	ds_read_b128 v[230:233], v198 offset:21504
	v_mfma_f32_16x16x32_bf16 v[126:129], v[150:153], v[204:207], v[126:129]
	v_mfma_f32_16x16x32_bf16 v[122:125], v[158:161], v[204:207], v[122:125]
	v_mfma_f32_16x16x32_bf16 v[110:113], v[146:149], v[208:211], v[110:113]
	v_mfma_f32_16x16x32_bf16 v[106:109], v[154:157], v[208:211], v[106:109]
	v_mfma_f32_16x16x32_bf16 v[118:121], v[134:137], v[204:207], v[118:121]
	v_mfma_f32_16x16x32_bf16 v[114:117], v[142:145], v[204:207], v[114:117]
	ds_read_b128 v[204:207], v198 offset:22528
	ds_read_b128 v[234:237], v198 offset:23552
	global_load_lds_dwordx4 v[224:225], off
	v_mfma_f32_16x16x32_bf16 v[94:97], v[130:133], v[208:211], v[94:97]
	s_add_i32 m0, s79, 0x2000
	s_add_u32 s80, s72, 0x10000
	s_addc_u32 s81, s73, 0
	v_mfma_f32_16x16x32_bf16 v[90:93], v[138:141], v[208:211], v[90:93]
	s_add_i32 s79, s76, s38
	global_load_lds_dwordx4 v[238:239], off
	v_lshl_add_u64 v[208:209], s[80:81], 0, v[184:185]
	s_mov_b32 m0, s79
	v_mfma_f32_16x16x32_bf16 v[110:113], v[150:153], v[178:181], v[110:113]
	global_load_lds_dwordx4 v[208:209], off
	s_add_i32 m0, s79, 0x2000
	v_mfma_f32_16x16x32_bf16 v[106:109], v[158:161], v[178:181], v[106:109]
	v_mfma_f32_16x16x32_bf16 v[94:97], v[134:137], v[178:181], v[94:97]
	v_mfma_f32_16x16x32_bf16 v[90:93], v[142:145], v[178:181], v[90:93]
	v_lshl_add_u64 v[178:179], s[80:81], 0, v[188:189]
	global_load_lds_dwordx4 v[178:179], off
	s_mov_b32 m0, s34
	v_mfma_f32_16x16x32_bf16 v[102:105], v[146:149], v[174:177], v[102:105]
	global_load_lds_dwordx4 v[240:241], off
	s_mov_b32 m0, s39
	v_mfma_f32_16x16x32_bf16 v[98:101], v[154:157], v[174:177], v[98:101]
	global_load_lds_dwordx4 v[242:243], off
	s_cmp_lg_u32 s78, 0
	s_cbranch_scc0 .Lqx7
	s_waitcnt vmcnt(8)

.Lqx7:
	s_cmp_eq_u32 s65, 0
	s_cbranch_scc1 .Lqy7
	s_waitcnt vmcnt(24)
	s_branch .Lre7

; #define PG8_STAGE(bufoff, gbase, voff) do { _Pragma("unroll") for (int _i = 0; _i < 2; ++_i) \
;         __builtin_amdgcn_global_load_lds((const unsigned*)((const char*)(gbase) + (voff)[_i]), (LAS unsigned*)(lds + (bufoff) + ldsw + _i * 8192), 16, 0, 0); } while (0)
; #define PG8_LDA(dst, b, h) do { _Pragma("unroll") for (int m = 0; m < 4; ++m) _Pragma("unroll") for (int k = 0; k < 2; ++k) dst[m][k] = *(const LAS bf16x8*)(lds + PG8_SA(b, h) + aoff + m * 2048 + k * 1024); } while (0)
; #define PG8_LDB(dst, b, h) do { _Pragma("unroll") for (int n = 0; n < 2; ++n) _Pragma("unroll") for (int k = 0; k < 2; ++k) dst[n][k] = *(const LAS bf16x8*)(lds + PG8_SB(b, h) + boff + n * 2048 + k * 1024); } while (0)
; #define PG8_MMA(ai, bj, At, Bt) do { __builtin_amdgcn_s_setprio(1); _Pragma("unroll") for (int m = 0; m < 4; ++m) _Pragma("unroll") for (int n = 0; n < 2; ++n) _Pragma("unroll") for (int k = 0; k < 2; ++k) \
;         acc[ai][bj][m][n] = __builtin_amdgcn_mfma_f32_16x16x32_bf16(Bt[n][k], At[m][k], acc[ai][bj][m][n], 0, 0, 0); __builtin_amdgcn_s_setprio(0); } while (0)
; #define PG8_WAIT_L(n) asm volatile("s_waitcnt lgkmcnt(" #n ")" ::: "memory")
; #define PG8_BAR __builtin_amdgcn_s_barrier()
; #define PG8_FLAG(v) do { } while (0)
; #define PG8_SCHED __builtin_amdgcn_sched_barrier(0)
; template <class Epi, class Sched, bool APERM, bool ABLK = false, bool RELAX = true>
; __device__ __forceinline__ void gemm_phase(LAS unsigned char* lds, const Gemm g, const Sched& S, const Epi& E) {
;     ...
;             const bool last = (t == nt - 2);
;             const char* a1 = cA + (size_t)(t + 1) * kstepA;
;             const char* a2 = last ? nA : cA + (size_t)(t + 2) * kstepA; const char* b2 = last ? nB : cB + (size_t)(t + 2) * kstep;
;             const char* a3 = a2 + kstepA; const char* b3 = b2 + kstep;
;             PG8_LDB(B0, 0, 0); PG8_LDB(B1, 0, 1); PG8_SCHED; PG8_LDA(At, 0, 0); PG8_STAGE(PG8_SA(1, 1), a1 + hstepA, voffA);
;             PG8_WAIT_V8R; PG8_WAIT_L(0); PG8_BAR; PG8_MMA(0, 0, At, B0); PG8_MMA(0, 1, At, B1); PG8_BAR; PG8_SCHED;
;             PG8_LDA(At, 0, 1); PG8_STAGE(PG8_SB(0, 0), b2, voffB); PG8_STAGE(PG8_SB(0, 1), b2 + hstepB, voffB); PG8_STAGE(PG8_SA(0, 0), a2, voffA);
;             PG8_WAIT_V8R; PG8_FLAG(0u); PG8_WAIT_L(0); PG8_BAR; PG8_MMA(1, 0, At, B0); PG8_MMA(1, 1, At, B1); PG8_BAR; PG8_SCHED;
.LBB0_861:
	ds_read_b128 v[144:147], v150
	ds_read_b128 v[154:157], v150 offset:1024
	ds_read_b128 v[158:161], v150 offset:2048
	ds_read_b128 v[162:165], v150 offset:3072
	ds_read_b128 v[166:169], v151
	ds_read_b128 v[170:173], v151 offset:1024
	ds_read_b128 v[174:177], v151 offset:2048
	ds_read_b128 v[178:181], v151 offset:3072
	s_add_i32 s82, s62, 2
	s_add_u32 s63, s60, 0xfffe0080
	s_addc_u32 s64, s61, -1
	s_cmp_eq_u32 s62, 4
	s_cselect_b32 s62, s79, s80
	s_cselect_b32 s65, s77, s64
	s_cselect_b32 s64, s78, s63
	s_cselect_b32 s63, s5, s81
	v_lshl_add_u64 v[214:215], s[60:61], 0, v[140:141]
	s_add_i32 m0, s3, 0xc000
	ds_read_b128 v[182:185], v152
	ds_read_b128 v[186:189], v152 offset:1024
	ds_read_b128 v[190:193], v152 offset:2048
	ds_read_b128 v[194:197], v152 offset:3072
	ds_read_b128 v[198:201], v152 offset:4096
	ds_read_b128 v[202:205], v152 offset:5120
	ds_read_b128 v[206:209], v152 offset:6144
	ds_read_b128 v[210:213], v152 offset:7168
	global_load_lds_dwordx4 v[214:215], off
	v_lshl_add_u64 v[214:215], s[60:61], 0, v[142:143]
	s_add_i32 m0, s3, 0xe000
	s_nop 0
	global_load_lds_dwordx4 v[214:215], off
	s_cmp_lg_u32 s82, 0
	s_cbranch_scc0 .Lqx8
	s_waitcnt vmcnt(8)
.Lre8:
	s_waitcnt lgkmcnt(0)
	s_barrier
	s_setprio 1
	s_waitcnt lgkmcnt(0)
	v_mfma_f32_16x16x32_bf16 v[126:129], v[144:147], v[182:185], v[126:129]
	v_mfma_f32_16x16x32_bf16 v[122:125], v[158:161], v[182:185], v[122:125]
	v_mfma_f32_16x16x32_bf16 v[118:121], v[144:147], v[190:193], v[118:121]
	v_mfma_f32_16x16x32_bf16 v[114:117], v[158:161], v[190:193], v[114:117]
	v_mfma_f32_16x16x32_bf16 v[110:113], v[144:147], v[198:201], v[110:113]
	v_mfma_f32_16x16x32_bf16 v[106:109], v[158:161], v[198:201], v[106:109]
	v_mfma_f32_16x16x32_bf16 v[102:105], v[144:147], v[206:209], v[102:105]
	v_mfma_f32_16x16x32_bf16 v[98:101], v[158:161], v[206:209], v[98:101]
	v_mfma_f32_16x16x32_bf16 v[126:129], v[154:157], v[186:189], v[126:129]
	v_mfma_f32_16x16x32_bf16 v[122:125], v[162:165], v[186:189], v[122:125]
	v_mfma_f32_16x16x32_bf16 v[118:121], v[154:157], v[194:197], v[118:121]
	v_mfma_f32_16x16x32_bf16 v[114:117], v[162:165], v[194:197], v[114:117]
	v_mfma_f32_16x16x32_bf16 v[110:113], v[154:157], v[202:205], v[110:113]
	v_mfma_f32_16x16x32_bf16 v[106:109], v[162:165], v[202:205], v[106:109]
	v_mfma_f32_16x16x32_bf16 v[102:105], v[154:157], v[210:213], v[102:105]
	v_mfma_f32_16x16x32_bf16 v[98:101], v[162:165], v[210:213], v[98:101]
	s_setprio 0
	s_setprio 1
	v_mfma_f32_16x16x32_bf16 v[62:65], v[166:169], v[182:185], v[62:65]
	v_mfma_f32_16x16x32_bf16 v[58:61], v[174:177], v[182:185], v[58:61]
	v_mfma_f32_16x16x32_bf16 v[54:57], v[166:169], v[190:193], v[54:57]
	v_mfma_f32_16x16x32_bf16 v[50:53], v[174:177], v[190:193], v[50:53]
	v_mfma_f32_16x16x32_bf16 v[46:49], v[166:169], v[198:201], v[46:49]
	v_mfma_f32_16x16x32_bf16 v[42:45], v[174:177], v[198:201], v[42:45]
	v_mfma_f32_16x16x32_bf16 v[38:41], v[166:169], v[206:209], v[38:41]
	v_mfma_f32_16x16x32_bf16 v[34:37], v[174:177], v[206:209], v[34:37]
	v_mfma_f32_16x16x32_bf16 v[62:65], v[170:173], v[186:189], v[62:65]
	v_mfma_f32_16x16x32_bf16 v[58:61], v[178:181], v[186:189], v[58:61]
	v_mfma_f32_16x16x32_bf16 v[54:57], v[170:173], v[194:197], v[54:57]
	v_mfma_f32_16x16x32_bf16 v[50:53], v[178:181], v[194:197], v[50:53]
	v_mfma_f32_16x16x32_bf16 v[46:49], v[170:173], v[202:205], v[46:49]
	v_mfma_f32_16x16x32_bf16 v[42:45], v[178:181], v[202:205], v[42:45]
	v_mfma_f32_16x16x32_bf16 v[38:41], v[170:173], v[210:213], v[38:41]
	v_mfma_f32_16x16x32_bf16 v[34:37], v[178:181], v[210:213], v[34:37]
	s_setprio 0
	s_barrier
	s_add_i32 s83, s71, s45
	v_lshl_add_u64 v[214:215], s[62:63], 0, v[134:135]
	s_mov_b32 m0, s83
	ds_read_b128 v[182:185], v152 offset:16384
	ds_read_b128 v[186:189], v152 offset:17408
	ds_read_b128 v[190:193], v152 offset:18432
	ds_read_b128 v[194:197], v152 offset:19456
	ds_read_b128 v[198:201], v152 offset:20480
	ds_read_b128 v[202:205], v152 offset:21504
	ds_read_b128 v[206:209], v152 offset:22528
	ds_read_b128 v[210:213], v152 offset:23552
	global_load_lds_dwordx4 v[214:215], off
	s_add_i32 m0, s83, 0x2000
	s_add_u32 s86, s62, 0x20000
	v_lshl_add_u64 v[216:217], s[62:63], 0, v[130:131]
	s_addc_u32 s87, s63, 0
	s_add_i32 s83, s31, s45
	global_load_lds_dwordx4 v[216:217], off
	v_lshl_add_u64 v[218:219], s[86:87], 0, v[134:135]
	s_mov_b32 m0, s83
	v_lshl_add_u64 v[220:221], s[64:65], 0, v[132:133]
	global_load_lds_dwordx4 v[218:219], off
	v_lshl_add_u64 v[218:219], s[86:87], 0, v[130:131]
	s_add_i32 m0, s83, 0x2000
	s_nop 0
	global_load_lds_dwordx4 v[218:219], off
	v_lshl_add_u64 v[218:219], s[64:65], 0, v[136:137]
	s_mov_b32 m0, s3
	s_nop 0
	global_load_lds_dwordx4 v[218:219], off
	s_mov_b32 m0, s46
	s_nop 0
	global_load_lds_dwordx4 v[220:221], off
	s_cmp_lg_u32 s82, 0
	s_cbranch_scc0 .Lqx9
	s_waitcnt vmcnt(8)

.Lqx9:
	s_cmp_eq_u32 s76, 0
	s_cbranch_scc1 .Lqy9
	s_waitcnt vmcnt(24)
	s_branch .Lre9

; #define PG8_STAGE(bufoff, gbase, voff) do { _Pragma("unroll") for (int _i = 0; _i < 2; ++_i) \
;         __builtin_amdgcn_global_load_lds((const unsigned*)((const char*)(gbase) + (voff)[_i]), (LAS unsigned*)(lds + (bufoff) + ldsw + _i * 8192), 16, 0, 0); } while (0)
; #define PG8_LDA(dst, b, h) do { _Pragma("unroll") for (int m = 0; m < 4; ++m) _Pragma("unroll") for (int k = 0; k < 2; ++k) dst[m][k] = *(const LAS bf16x8*)(lds + PG8_SA(b, h) + aoff + m * 2048 + k * 1024); } while (0)
; #define PG8_LDB(dst, b, h) do { _Pragma("unroll") for (int n = 0; n < 2; ++n) _Pragma("unroll") for (int k = 0; k < 2; ++k) dst[n][k] = *(const LAS bf16x8*)(lds + PG8_SB(b, h) + boff + n * 2048 + k * 1024); } while (0)
; #define PG8_MMA(ai, bj, At, Bt) do { __builtin_amdgcn_s_setprio(1); _Pragma("unroll") for (int m = 0; m < 4; ++m) _Pragma("unroll") for (int n = 0; n < 2; ++n) _Pragma("unroll") for (int k = 0; k < 2; ++k) \
;         acc[ai][bj][m][n] = __builtin_amdgcn_mfma_f32_16x16x32_bf16(Bt[n][k], At[m][k], acc[ai][bj][m][n], 0, 0, 0); __builtin_amdgcn_s_setprio(0); } while (0)
; #define PG8_WAIT_L(n) asm volatile("s_waitcnt lgkmcnt(" #n ")" ::: "memory")
; #define PG8_BAR __builtin_amdgcn_s_barrier()
; #define PG8_FLAG(v) do { } while (0)
; #define PG8_SCHED __builtin_amdgcn_sched_barrier(0)
; template <class Epi, class Sched, bool APERM, bool ABLK = false, bool RELAX = true>
; __device__ __forceinline__ void gemm_phase(LAS unsigned char* lds, const Gemm g, const Sched& S, const Epi& E) {
;     ...
;             const bool last = (t == nt - 2);
;             const char* a1 = cA + (size_t)(t + 1) * kstepA;
;             const char* a2 = last ? nA : cA + (size_t)(t + 2) * kstepA; const char* b2 = last ? nB : cB + (size_t)(t + 2) * kstep;
;             const char* a3 = a2 + kstepA; const char* b3 = b2 + kstep;
;             PG8_LDB(B0, 0, 0); PG8_LDB(B1, 0, 1); PG8_SCHED; PG8_LDA(At, 0, 0); PG8_STAGE(PG8_SA(1, 1), a1 + hstepA, voffA);
;             PG8_WAIT_V8R; PG8_WAIT_L(0); PG8_BAR; PG8_MMA(0, 0, At, B0); PG8_MMA(0, 1, At, B1); PG8_BAR; PG8_SCHED;
;             PG8_LDA(At, 0, 1); PG8_STAGE(PG8_SB(0, 0), b2, voffB); PG8_STAGE(PG8_SB(0, 1), b2 + hstepB, voffB); PG8_STAGE(PG8_SA(0, 0), a2, voffA);
;             PG8_WAIT_V8R; PG8_FLAG(0u); PG8_WAIT_L(0); PG8_BAR; PG8_MMA(1, 0, At, B0); PG8_MMA(1, 1, At, B1); PG8_BAR; PG8_SCHED;
.LBB0_943:
	ds_read_b128 v[132:135], v212
	ds_read_b128 v[136:139], v212 offset:1024
	ds_read_b128 v[140:143], v212 offset:2048
	ds_read_b128 v[144:147], v212 offset:3072
	ds_read_b128 v[148:151], v213
	ds_read_b128 v[152:155], v213 offset:1024
	ds_read_b128 v[156:159], v213 offset:2048
	ds_read_b128 v[178:181], v213 offset:3072
	s_add_i32 s51, s59, 2
	s_add_u32 s61, s68, 0xfffe0080
	s_addc_u32 s70, s69, -1
	s_cmp_eq_u32 s59, 4
	s_cselect_b32 s73, s45, s70
	s_cselect_b32 s72, s46, s61
	s_cselect_b32 s71, s47, s50
	s_cselect_b32 s70, s48, s49
	v_lshl_add_u64 v[160:161], s[68:69], 0, v[170:171]
	s_add_i32 m0, s30, 0xc000
	ds_read_b128 v[182:185], v214
	ds_read_b128 v[186:189], v214 offset:1024
	ds_read_b128 v[190:193], v214 offset:2048
	ds_read_b128 v[194:197], v214 offset:3072
	ds_read_b128 v[198:201], v214 offset:4096
	ds_read_b128 v[202:205], v214 offset:5120
	ds_read_b128 v[206:209], v214 offset:6144
	ds_read_b128 v[216:219], v214 offset:7168
	global_load_lds_dwordx4 v[160:161], off
	v_lshl_add_u64 v[160:161], s[68:69], 0, v[172:173]
	s_add_i32 m0, s30, 0xe000
	s_nop 0
	global_load_lds_dwordx4 v[160:161], off
	s_cmp_lg_u32 s51, 0
	s_cbranch_scc0 .Lqx10
	s_waitcnt vmcnt(8)
.Lre10:
	s_waitcnt lgkmcnt(0)
	s_barrier
	s_setprio 1
	s_waitcnt lgkmcnt(0)
	v_mfma_f32_16x16x32_bf16 v[126:129], v[132:135], v[182:185], v[126:129]
	v_mfma_f32_16x16x32_bf16 v[122:125], v[140:143], v[182:185], v[122:125]
	v_mfma_f32_16x16x32_bf16 v[118:121], v[132:135], v[190:193], v[118:121]
	v_mfma_f32_16x16x32_bf16 v[114:117], v[140:143], v[190:193], v[114:117]
	v_mfma_f32_16x16x32_bf16 v[110:113], v[132:135], v[198:201], v[110:113]
	v_mfma_f32_16x16x32_bf16 v[106:109], v[140:143], v[198:201], v[106:109]
	v_mfma_f32_16x16x32_bf16 v[102:105], v[132:135], v[206:209], v[102:105]
	v_mfma_f32_16x16x32_bf16 v[98:101], v[140:143], v[206:209], v[98:101]
	v_mfma_f32_16x16x32_bf16 v[126:129], v[136:139], v[186:189], v[126:129]
	v_mfma_f32_16x16x32_bf16 v[122:125], v[144:147], v[186:189], v[122:125]
	v_mfma_f32_16x16x32_bf16 v[118:121], v[136:139], v[194:197], v[118:121]
	v_mfma_f32_16x16x32_bf16 v[114:117], v[144:147], v[194:197], v[114:117]
	v_mfma_f32_16x16x32_bf16 v[110:113], v[136:139], v[202:205], v[110:113]
	v_mfma_f32_16x16x32_bf16 v[106:109], v[144:147], v[202:205], v[106:109]
	v_mfma_f32_16x16x32_bf16 v[102:105], v[136:139], v[216:219], v[102:105]
	v_mfma_f32_16x16x32_bf16 v[98:101], v[144:147], v[216:219], v[98:101]
	s_setprio 0
	s_setprio 1
	v_mfma_f32_16x16x32_bf16 v[62:65], v[148:151], v[182:185], v[62:65]
	v_mfma_f32_16x16x32_bf16 v[58:61], v[156:159], v[182:185], v[58:61]
	v_mfma_f32_16x16x32_bf16 v[54:57], v[148:151], v[190:193], v[54:57]
	v_mfma_f32_16x16x32_bf16 v[50:53], v[156:159], v[190:193], v[50:53]
	v_mfma_f32_16x16x32_bf16 v[46:49], v[148:151], v[198:201], v[46:49]
	v_mfma_f32_16x16x32_bf16 v[42:45], v[156:159], v[198:201], v[42:45]
	v_mfma_f32_16x16x32_bf16 v[38:41], v[148:151], v[206:209], v[38:41]
	v_mfma_f32_16x16x32_bf16 v[34:37], v[156:159], v[206:209], v[34:37]
	v_mfma_f32_16x16x32_bf16 v[62:65], v[152:155], v[186:189], v[62:65]
	v_mfma_f32_16x16x32_bf16 v[58:61], v[178:181], v[186:189], v[58:61]
	v_mfma_f32_16x16x32_bf16 v[54:57], v[152:155], v[194:197], v[54:57]
	v_mfma_f32_16x16x32_bf16 v[50:53], v[178:181], v[194:197], v[50:53]
	v_mfma_f32_16x16x32_bf16 v[46:49], v[152:155], v[202:205], v[46:49]
	v_mfma_f32_16x16x32_bf16 v[42:45], v[178:181], v[202:205], v[42:45]
	v_mfma_f32_16x16x32_bf16 v[38:41], v[152:155], v[216:219], v[38:41]
	v_mfma_f32_16x16x32_bf16 v[34:37], v[178:181], v[216:219], v[34:37]
	s_setprio 0
	s_barrier
	s_add_i32 s59, s43, s29
	v_lshl_add_u64 v[160:161], s[70:71], 0, v[164:165]
	s_mov_b32 m0, s59
	ds_read_b128 v[182:185], v214 offset:16384
	ds_read_b128 v[186:189], v214 offset:17408
	ds_read_b128 v[190:193], v214 offset:18432
	ds_read_b128 v[194:197], v214 offset:19456
	ds_read_b128 v[198:201], v214 offset:20480
	ds_read_b128 v[202:205], v214 offset:21504
	ds_read_b128 v[206:209], v214 offset:22528
	ds_read_b128 v[216:219], v214 offset:23552
	global_load_lds_dwordx4 v[160:161], off
	s_add_i32 m0, s59, 0x2000
	s_add_u32 s74, s70, 0x20000
	v_lshl_add_u64 v[220:221], s[70:71], 0, v[168:169]
	s_addc_u32 s75, s71, 0
	s_add_i32 s59, s31, s29
	global_load_lds_dwordx4 v[220:221], off
	v_lshl_add_u64 v[222:223], s[74:75], 0, v[164:165]
	s_mov_b32 m0, s59
	v_lshl_add_u64 v[224:225], s[72:73], 0, v[166:167]
	global_load_lds_dwordx4 v[222:223], off
	v_lshl_add_u64 v[222:223], s[74:75], 0, v[168:169]
	s_add_i32 m0, s59, 0x2000
	s_nop 0
	global_load_lds_dwordx4 v[222:223], off
	v_lshl_add_u64 v[222:223], s[72:73], 0, v[162:163]
	s_mov_b32 m0, s30
	s_nop 0
	global_load_lds_dwordx4 v[222:223], off
	s_mov_b32 m0, s34
	s_nop 0
	global_load_lds_dwordx4 v[224:225], off
	s_cmp_lg_u32 s51, 0
	s_cbranch_scc0 .Lqx11
	s_waitcnt vmcnt(8)

.Lqx11:
	s_cmp_eq_u32 s67, 0
	s_cbranch_scc1 .Lqy11
	s_waitcnt vmcnt(24)
	s_branch .Lre11

; #define PG8_STAGE(bufoff, gbase, voff) do { _Pragma("unroll") for (int _i = 0; _i < 2; ++_i) \
;         __builtin_amdgcn_global_load_lds((const unsigned*)((const char*)(gbase) + (voff)[_i]), (LAS unsigned*)(lds + (bufoff) + ldsw + _i * 8192), 16, 0, 0); } while (0)
; #define PG8_LDA(dst, b, h) do { _Pragma("unroll") for (int m = 0; m < 4; ++m) _Pragma("unroll") for (int k = 0; k < 2; ++k) dst[m][k] = *(const LAS bf16x8*)(lds + PG8_SA(b, h) + aoff + m * 2048 + k * 1024); } while (0)
; #define PG8_LDB(dst, b, h) do { _Pragma("unroll") for (int n = 0; n < 2; ++n) _Pragma("unroll") for (int k = 0; k < 2; ++k) dst[n][k] = *(const LAS bf16x8*)(lds + PG8_SB(b, h) + boff + n * 2048 + k * 1024); } while (0)
; #define PG8_MMA(ai, bj, At, Bt) do { __builtin_amdgcn_s_setprio(1); _Pragma("unroll") for (int m = 0; m < 4; ++m) _Pragma("unroll") for (int n = 0; n < 2; ++n) _Pragma("unroll") for (int k = 0; k < 2; ++k) \
;         acc[ai][bj][m][n] = __builtin_amdgcn_mfma_f32_16x16x32_bf16(Bt[n][k], At[m][k], acc[ai][bj][m][n], 0, 0, 0); __builtin_amdgcn_s_setprio(0); } while (0)
; #define PG8_WAIT_L(n) asm volatile("s_waitcnt lgkmcnt(" #n ")" ::: "memory")
; #define PG8_BAR __builtin_amdgcn_s_barrier()
; #define PG8_FLAG(v) do { } while (0)
; #define PG8_SCHED __builtin_amdgcn_sched_barrier(0)
; template <class Epi, class Sched, bool APERM, bool ABLK = false, bool RELAX = true>
; __device__ __forceinline__ void gemm_phase(LAS unsigned char* lds, const Gemm g, const Sched& S, const Epi& E) {
;     ...
;             const bool last = (t == nt - 2);
;             const char* a1 = cA + (size_t)(t + 1) * kstepA;
;             const char* a2 = last ? nA : cA + (size_t)(t + 2) * kstepA; const char* b2 = last ? nB : cB + (size_t)(t + 2) * kstep;
;             const char* a3 = a2 + kstepA; const char* b3 = b2 + kstep;
;             PG8_LDB(B0, 0, 0); PG8_LDB(B1, 0, 1); PG8_SCHED; PG8_LDA(At, 0, 0); PG8_STAGE(PG8_SA(1, 1), a1 + hstepA, voffA);
;             PG8_WAIT_V8R; PG8_WAIT_L(0); PG8_BAR; PG8_MMA(0, 0, At, B0); PG8_MMA(0, 1, At, B1); PG8_BAR; PG8_SCHED;
;             PG8_LDA(At, 0, 1); PG8_STAGE(PG8_SB(0, 0), b2, voffB); PG8_STAGE(PG8_SB(0, 1), b2 + hstepB, voffB); PG8_STAGE(PG8_SA(0, 0), a2, voffA);
;             PG8_WAIT_V8R; PG8_FLAG(0u); PG8_WAIT_L(0); PG8_BAR; PG8_MMA(1, 0, At, B0); PG8_MMA(1, 1, At, B1); PG8_BAR; PG8_SCHED;
.LBB0_1017:
	ds_read_b128 v[130:133], v180
	ds_read_b128 v[134:137], v180 offset:1024
	ds_read_b128 v[154:157], v180 offset:2048
	ds_read_b128 v[158:161], v180 offset:3072
	ds_read_b128 v[162:165], v181
	ds_read_b128 v[166:169], v181 offset:1024
	ds_read_b128 v[170:173], v181 offset:2048
	ds_read_b128 v[174:177], v181 offset:3072
	s_add_i32 s68, s60, 2
	s_add_u32 s61, s58, 0xfffc0080
	s_addc_u32 s62, s59, -1
	s_cmp_eq_u32 s60, 12
	s_cselect_b32 s60, s65, s66
	s_cselect_b32 s63, s17, s62
	s_cselect_b32 s62, s64, s61
	s_cselect_b32 s61, s15, s67
	v_lshl_add_u64 v[216:217], s[58:59], 0, v[146:147]
	s_add_i32 m0, s35, 0xc000
	ds_read_b128 v[184:187], v182
	ds_read_b128 v[188:191], v182 offset:1024
	ds_read_b128 v[192:195], v182 offset:2048
	ds_read_b128 v[196:199], v182 offset:3072
	ds_read_b128 v[200:203], v182 offset:4096
	ds_read_b128 v[204:207], v182 offset:5120
	ds_read_b128 v[208:211], v182 offset:6144
	ds_read_b128 v[212:215], v182 offset:7168
	global_load_lds_dwordx4 v[216:217], off
	v_lshl_add_u64 v[216:217], s[58:59], 0, v[148:149]
	s_add_i32 m0, s35, 0xe000
	s_nop 0
	global_load_lds_dwordx4 v[216:217], off
	s_cmp_lg_u32 s68, 0
	s_cbranch_scc0 .Lqx12
	s_waitcnt vmcnt(8)
.Lre12:
	s_waitcnt lgkmcnt(0)
	s_barrier
	s_setprio 1
	s_waitcnt lgkmcnt(0)
	v_mfma_f32_16x16x32_bf16 v[126:129], v[130:133], v[184:187], v[126:129]
	v_mfma_f32_16x16x32_bf16 v[122:125], v[154:157], v[184:187], v[122:125]
	v_mfma_f32_16x16x32_bf16 v[118:121], v[130:133], v[192:195], v[118:121]
	v_mfma_f32_16x16x32_bf16 v[114:117], v[154:157], v[192:195], v[114:117]
	v_mfma_f32_16x16x32_bf16 v[110:113], v[130:133], v[200:203], v[110:113]
	v_mfma_f32_16x16x32_bf16 v[106:109], v[154:157], v[200:203], v[106:109]
	v_mfma_f32_16x16x32_bf16 v[102:105], v[130:133], v[208:211], v[102:105]
	v_mfma_f32_16x16x32_bf16 v[98:101], v[154:157], v[208:211], v[98:101]
	v_mfma_f32_16x16x32_bf16 v[126:129], v[134:137], v[188:191], v[126:129]
	v_mfma_f32_16x16x32_bf16 v[122:125], v[158:161], v[188:191], v[122:125]
	v_mfma_f32_16x16x32_bf16 v[118:121], v[134:137], v[196:199], v[118:121]
	v_mfma_f32_16x16x32_bf16 v[114:117], v[158:161], v[196:199], v[114:117]
	v_mfma_f32_16x16x32_bf16 v[110:113], v[134:137], v[204:207], v[110:113]
	v_mfma_f32_16x16x32_bf16 v[106:109], v[158:161], v[204:207], v[106:109]
	v_mfma_f32_16x16x32_bf16 v[102:105], v[134:137], v[212:215], v[102:105]
	v_mfma_f32_16x16x32_bf16 v[98:101], v[158:161], v[212:215], v[98:101]
	s_setprio 0
	s_setprio 1
	v_mfma_f32_16x16x32_bf16 v[62:65], v[162:165], v[184:187], v[62:65]
	v_mfma_f32_16x16x32_bf16 v[58:61], v[170:173], v[184:187], v[58:61]
	v_mfma_f32_16x16x32_bf16 v[54:57], v[162:165], v[192:195], v[54:57]
	v_mfma_f32_16x16x32_bf16 v[50:53], v[170:173], v[192:195], v[50:53]
	v_mfma_f32_16x16x32_bf16 v[46:49], v[162:165], v[200:203], v[46:49]
	v_mfma_f32_16x16x32_bf16 v[42:45], v[170:173], v[200:203], v[42:45]
	v_mfma_f32_16x16x32_bf16 v[38:41], v[162:165], v[208:211], v[38:41]
	v_mfma_f32_16x16x32_bf16 v[34:37], v[170:173], v[208:211], v[34:37]
	v_mfma_f32_16x16x32_bf16 v[62:65], v[166:169], v[188:191], v[62:65]
	v_mfma_f32_16x16x32_bf16 v[58:61], v[174:177], v[188:191], v[58:61]
	v_mfma_f32_16x16x32_bf16 v[54:57], v[166:169], v[196:199], v[54:57]
	v_mfma_f32_16x16x32_bf16 v[50:53], v[174:177], v[196:199], v[50:53]
	v_mfma_f32_16x16x32_bf16 v[46:49], v[166:169], v[204:207], v[46:49]
	v_mfma_f32_16x16x32_bf16 v[42:45], v[174:177], v[204:207], v[42:45]
	v_mfma_f32_16x16x32_bf16 v[38:41], v[166:169], v[212:215], v[38:41]
	v_mfma_f32_16x16x32_bf16 v[34:37], v[174:177], v[212:215], v[34:37]
	s_setprio 0
	s_barrier
	s_add_i32 s69, s48, s34
	v_lshl_add_u64 v[216:217], s[60:61], 0, v[140:141]
	s_mov_b32 m0, s69
	ds_read_b128 v[184:187], v182 offset:16384
	ds_read_b128 v[188:191], v182 offset:17408
	ds_read_b128 v[192:195], v182 offset:18432
	ds_read_b128 v[196:199], v182 offset:19456
	ds_read_b128 v[200:203], v182 offset:20480
	ds_read_b128 v[204:207], v182 offset:21504
	ds_read_b128 v[208:211], v182 offset:22528
	ds_read_b128 v[212:215], v182 offset:23552
	global_load_lds_dwordx4 v[216:217], off
	s_add_i32 m0, s69, 0x2000
	s_add_u32 s70, s60, 0x40000
	v_lshl_add_u64 v[218:219], s[60:61], 0, v[144:145]
	s_addc_u32 s71, s61, 0
	s_add_i32 s69, s49, s34
	global_load_lds_dwordx4 v[218:219], off
	v_lshl_add_u64 v[220:221], s[70:71], 0, v[140:141]
	s_mov_b32 m0, s69
	v_lshl_add_u64 v[222:223], s[62:63], 0, v[142:143]
	global_load_lds_dwordx4 v[220:221], off
	v_lshl_add_u64 v[220:221], s[70:71], 0, v[144:145]
	s_add_i32 m0, s69, 0x2000
	s_nop 0
	global_load_lds_dwordx4 v[220:221], off
	v_lshl_add_u64 v[220:221], s[62:63], 0, v[138:139]
	s_mov_b32 m0, s35
	s_nop 0
	global_load_lds_dwordx4 v[220:221], off
	s_mov_b32 m0, s36
	s_nop 0
	global_load_lds_dwordx4 v[222:223], off
	s_cmp_lg_u32 s68, 0
	s_cbranch_scc0 .Lqx13
	s_waitcnt vmcnt(8)

.Lqx13:
	s_cmp_eq_u32 s5, 0
	s_cbranch_scc1 .Lqy13
	s_waitcnt vmcnt(24)
	s_branch .Lre13

; #define PG8_STAGE(bufoff, gbase, voff) do { _Pragma("unroll") for (int _i = 0; _i < 2; ++_i) \
;         __builtin_amdgcn_global_load_lds((const unsigned*)((const char*)(gbase) + (voff)[_i]), (LAS unsigned*)(lds + (bufoff) + ldsw + _i * 8192), 16, 0, 0); } while (0)
; #define PG8_LDA(dst, b, h) do { _Pragma("unroll") for (int m = 0; m < 4; ++m) _Pragma("unroll") for (int k = 0; k < 2; ++k) dst[m][k] = *(const LAS bf16x8*)(lds + PG8_SA(b, h) + aoff + m * 2048 + k * 1024); } while (0)
; #define PG8_LDB(dst, b, h) do { _Pragma("unroll") for (int n = 0; n < 2; ++n) _Pragma("unroll") for (int k = 0; k < 2; ++k) dst[n][k] = *(const LAS bf16x8*)(lds + PG8_SB(b, h) + boff + n * 2048 + k * 1024); } while (0)
; #define PG8_MMA(ai, bj, At, Bt) do { __builtin_amdgcn_s_setprio(1); _Pragma("unroll") for (int m = 0; m < 4; ++m) _Pragma("unroll") for (int n = 0; n < 2; ++n) _Pragma("unroll") for (int k = 0; k < 2; ++k) \
;         acc[ai][bj][m][n] = __builtin_amdgcn_mfma_f32_16x16x32_bf16(Bt[n][k], At[m][k], acc[ai][bj][m][n], 0, 0, 0); __builtin_amdgcn_s_setprio(0); } while (0)
; #define PG8_WAIT_L(n) asm volatile("s_waitcnt lgkmcnt(" #n ")" ::: "memory")
; #define PG8_BAR __builtin_amdgcn_s_barrier()
; #define PG8_FLAG(v) do { } while (0)
; #define PG8_SCHED __builtin_amdgcn_sched_barrier(0)
; template <class Epi, class Sched, bool APERM, bool ABLK = false, bool RELAX = true>
; __device__ __forceinline__ void gemm_phase(LAS unsigned char* lds, const Gemm g, const Sched& S, const Epi& E) {
;     ...
;             const bool last = (t == nt - 2);
;             const char* a1 = cA + (size_t)(t + 1) * kstepA;
;             const char* a2 = last ? nA : cA + (size_t)(t + 2) * kstepA; const char* b2 = last ? nB : cB + (size_t)(t + 2) * kstep;
;             const char* a3 = a2 + kstepA; const char* b3 = b2 + kstep;
;             PG8_LDB(B0, 0, 0); PG8_LDB(B1, 0, 1); PG8_SCHED; PG8_LDA(At, 0, 0); PG8_STAGE(PG8_SA(1, 1), a1 + hstepA, voffA);
;             PG8_WAIT_V8R; PG8_WAIT_L(0); PG8_BAR; PG8_MMA(0, 0, At, B0); PG8_MMA(0, 1, At, B1); PG8_BAR; PG8_SCHED;
;             PG8_LDA(At, 0, 1); PG8_STAGE(PG8_SB(0, 0), b2, voffB); PG8_STAGE(PG8_SB(0, 1), b2 + hstepB, voffB); PG8_STAGE(PG8_SA(0, 0), a2, voffA);
;             PG8_WAIT_V8R; PG8_FLAG(0u); PG8_WAIT_L(0); PG8_BAR; PG8_MMA(1, 0, At, B0); PG8_MMA(1, 1, At, B1); PG8_BAR; PG8_SCHED;
.LBB0_1095:
	ds_read_b128 v[148:151], v143
	ds_read_b128 v[152:155], v143 offset:1024
	ds_read_b128 v[156:159], v143 offset:2048
	ds_read_b128 v[160:163], v143 offset:3072
	ds_read_b128 v[164:167], v144
	ds_read_b128 v[168:171], v144 offset:1024
	ds_read_b128 v[172:175], v144 offset:2048
	ds_read_b128 v[176:179], v144 offset:3072
	s_add_i32 s40, s40, 2
	s_add_u32 s12, s8, s10
	s_addc_u32 s13, s9, s11
	s_add_u32 s12, s12, 0xdf00100
	s_addc_u32 s13, s13, 0
	s_add_u32 s51, s38, s10
	s_addc_u32 s54, s39, s11
	s_cmpk_eq_i32 s10, 0x700
	s_cselect_b32 s15, s5, s13
	s_cselect_b32 s14, s4, s12
	s_cselect_b32 s13, s1, s54
	s_cselect_b32 s12, s0, s51
	s_mov_b32 m0, s41
	v_lshl_add_u64 v[212:213], v[138:139], 0, s[10:11]
	ds_read_b128 v[180:183], v145
	ds_read_b128 v[184:187], v145 offset:1024
	ds_read_b128 v[188:191], v145 offset:2048
	ds_read_b128 v[192:195], v145 offset:3072
	ds_read_b128 v[196:199], v145 offset:4096
	ds_read_b128 v[200:203], v145 offset:5120
	ds_read_b128 v[204:207], v145 offset:6144
	ds_read_b128 v[208:211], v145 offset:7168
	global_load_lds_dwordx4 v[212:213], off
	v_lshl_add_u64 v[212:213], v[140:141], 0, s[10:11]
	s_mov_b32 m0, s42
	s_nop 0
	global_load_lds_dwordx4 v[212:213], off
	s_cmp_lg_u32 s40, 0
	s_cbranch_scc0 .Lqx14
	s_waitcnt vmcnt(8)
.Lre14:
	s_waitcnt lgkmcnt(0)
	s_barrier
	s_setprio 1
	s_waitcnt lgkmcnt(0)
	v_mfma_f32_16x16x32_bf16 v[126:129], v[148:151], v[180:183], v[126:129]
	v_mfma_f32_16x16x32_bf16 v[122:125], v[156:159], v[180:183], v[122:125]
	v_mfma_f32_16x16x32_bf16 v[118:121], v[148:151], v[188:191], v[118:121]
	v_mfma_f32_16x16x32_bf16 v[114:117], v[156:159], v[188:191], v[114:117]
	v_mfma_f32_16x16x32_bf16 v[110:113], v[148:151], v[196:199], v[110:113]
	v_mfma_f32_16x16x32_bf16 v[106:109], v[156:159], v[196:199], v[106:109]
	v_mfma_f32_16x16x32_bf16 v[102:105], v[148:151], v[204:207], v[102:105]
	v_mfma_f32_16x16x32_bf16 v[98:101], v[156:159], v[204:207], v[98:101]
	v_mfma_f32_16x16x32_bf16 v[126:129], v[152:155], v[184:187], v[126:129]
	v_mfma_f32_16x16x32_bf16 v[122:125], v[160:163], v[184:187], v[122:125]
	v_mfma_f32_16x16x32_bf16 v[118:121], v[152:155], v[192:195], v[118:121]
	v_mfma_f32_16x16x32_bf16 v[114:117], v[160:163], v[192:195], v[114:117]
	v_mfma_f32_16x16x32_bf16 v[110:113], v[152:155], v[200:203], v[110:113]
	v_mfma_f32_16x16x32_bf16 v[106:109], v[160:163], v[200:203], v[106:109]
	v_mfma_f32_16x16x32_bf16 v[102:105], v[152:155], v[208:211], v[102:105]
	v_mfma_f32_16x16x32_bf16 v[98:101], v[160:163], v[208:211], v[98:101]
	s_setprio 0
	s_setprio 1
	v_mfma_f32_16x16x32_bf16 v[62:65], v[164:167], v[180:183], v[62:65]
	v_mfma_f32_16x16x32_bf16 v[58:61], v[172:175], v[180:183], v[58:61]
	v_mfma_f32_16x16x32_bf16 v[54:57], v[164:167], v[188:191], v[54:57]
	v_mfma_f32_16x16x32_bf16 v[50:53], v[172:175], v[188:191], v[50:53]
	v_mfma_f32_16x16x32_bf16 v[46:49], v[164:167], v[196:199], v[46:49]
	v_mfma_f32_16x16x32_bf16 v[42:45], v[172:175], v[196:199], v[42:45]
	v_mfma_f32_16x16x32_bf16 v[38:41], v[164:167], v[204:207], v[38:41]
	v_mfma_f32_16x16x32_bf16 v[34:37], v[172:175], v[204:207], v[34:37]
	v_mfma_f32_16x16x32_bf16 v[62:65], v[168:171], v[184:187], v[62:65]
	v_mfma_f32_16x16x32_bf16 v[58:61], v[176:179], v[184:187], v[58:61]
	v_mfma_f32_16x16x32_bf16 v[54:57], v[168:171], v[192:195], v[54:57]
	v_mfma_f32_16x16x32_bf16 v[50:53], v[176:179], v[192:195], v[50:53]
	v_mfma_f32_16x16x32_bf16 v[46:49], v[168:171], v[200:203], v[46:49]
	v_mfma_f32_16x16x32_bf16 v[42:45], v[176:179], v[200:203], v[42:45]
	v_mfma_f32_16x16x32_bf16 v[38:41], v[168:171], v[208:211], v[38:41]
	v_mfma_f32_16x16x32_bf16 v[34:37], v[176:179], v[208:211], v[34:37]
	s_setprio 0
	s_barrier
	s_mov_b32 m0, s43
	v_lshl_add_u64 v[212:213], s[12:13], 0, v[132:133]
	s_add_u32 s54, s12, 0x40000
	ds_read_b128 v[180:183], v145 offset:16384
	ds_read_b128 v[184:187], v145 offset:17408
	ds_read_b128 v[188:191], v145 offset:18432
	ds_read_b128 v[192:195], v145 offset:19456
	ds_read_b128 v[196:199], v145 offset:20480
	ds_read_b128 v[200:203], v145 offset:21504
	ds_read_b128 v[204:207], v145 offset:22528
	ds_read_b128 v[208:211], v145 offset:23552
	global_load_lds_dwordx4 v[212:213], off
	v_lshl_add_u64 v[214:215], s[12:13], 0, v[136:137]
	s_mov_b32 m0, s44
	s_addc_u32 s55, s13, 0
	global_load_lds_dwordx4 v[214:215], off
	v_lshl_add_u64 v[216:217], s[54:55], 0, v[132:133]
	s_mov_b32 m0, s45
	v_lshl_add_u64 v[218:219], s[14:15], 0, v[134:135]
	global_load_lds_dwordx4 v[216:217], off
	v_lshl_add_u64 v[216:217], s[54:55], 0, v[136:137]
	s_mov_b32 m0, s46
	s_nop 0
	global_load_lds_dwordx4 v[216:217], off
	v_lshl_add_u64 v[216:217], s[14:15], 0, v[130:131]
	s_mov_b32 m0, s19
	s_nop 0
	global_load_lds_dwordx4 v[216:217], off
	s_mov_b32 m0, s29
	s_nop 0
	global_load_lds_dwordx4 v[218:219], off
	s_cmp_lg_u32 s40, 0
	s_cbranch_scc0 .Lqx15
	s_waitcnt vmcnt(8)

.Lqx15:
	s_cmp_eq_u32 s34, 0
	s_cbranch_scc1 .Lqy15
	s_waitcnt vmcnt(24)
	s_branch .Lre15

; #define PG8_STAGE(bufoff, gbase, voff) do { _Pragma("unroll") for (int _i = 0; _i < 2; ++_i) \
;         __builtin_amdgcn_global_load_lds((const unsigned*)((const char*)(gbase) + (voff)[_i]), (LAS unsigned*)(lds + (bufoff) + ldsw + _i * 8192), 16, 0, 0); } while (0)
; #define PG8_LDA(dst, b, h) do { _Pragma("unroll") for (int m = 0; m < 4; ++m) _Pragma("unroll") for (int k = 0; k < 2; ++k) dst[m][k] = *(const LAS bf16x8*)(lds + PG8_SA(b, h) + aoff + m * 2048 + k * 1024); } while (0)
; #define PG8_LDB(dst, b, h) do { _Pragma("unroll") for (int n = 0; n < 2; ++n) _Pragma("unroll") for (int k = 0; k < 2; ++k) dst[n][k] = *(const LAS bf16x8*)(lds + PG8_SB(b, h) + boff + n * 2048 + k * 1024); } while (0)
; #define PG8_MMA(ai, bj, At, Bt) do { __builtin_amdgcn_s_setprio(1); _Pragma("unroll") for (int m = 0; m < 4; ++m) _Pragma("unroll") for (int n = 0; n < 2; ++n) _Pragma("unroll") for (int k = 0; k < 2; ++k) \
;         acc[ai][bj][m][n] = __builtin_amdgcn_mfma_f32_16x16x32_bf16(Bt[n][k], At[m][k], acc[ai][bj][m][n], 0, 0, 0); __builtin_amdgcn_s_setprio(0); } while (0)
; #define PG8_WAIT_L(n) asm volatile("s_waitcnt lgkmcnt(" #n ")" ::: "memory")
; #define PG8_BAR __builtin_amdgcn_s_barrier()
; #define PG8_FLAG(v) do { } while (0)
; #define PG8_SCHED __builtin_amdgcn_sched_barrier(0)
; template <class Epi, class Sched, bool APERM, bool ABLK = false, bool RELAX = true>
; __device__ __forceinline__ void gemm_phase(LAS unsigned char* lds, const Gemm g, const Sched& S, const Epi& E) {
;     ...
;             const bool last = (t == nt - 2);
;             const char* a1 = cA + (size_t)(t + 1) * kstepA;
;             const char* a2 = last ? nA : cA + (size_t)(t + 2) * kstepA; const char* b2 = last ? nB : cB + (size_t)(t + 2) * kstep;
;             const char* a3 = a2 + kstepA; const char* b3 = b2 + kstep;
;             PG8_LDB(B0, 0, 0); PG8_LDB(B1, 0, 1); PG8_SCHED; PG8_LDA(At, 0, 0); PG8_STAGE(PG8_SA(1, 1), a1 + hstepA, voffA);
;             PG8_WAIT_V8R; PG8_WAIT_L(0); PG8_BAR; PG8_MMA(0, 0, At, B0); PG8_MMA(0, 1, At, B1); PG8_BAR; PG8_SCHED;
;             PG8_LDA(At, 0, 1); PG8_STAGE(PG8_SB(0, 0), b2, voffB); PG8_STAGE(PG8_SB(0, 1), b2 + hstepB, voffB); PG8_STAGE(PG8_SA(0, 0), a2, voffA);
;             PG8_WAIT_V8R; PG8_FLAG(0u); PG8_WAIT_L(0); PG8_BAR; PG8_MMA(1, 0, At, B0); PG8_MMA(1, 1, At, B1); PG8_BAR; PG8_SCHED;
.LBB0_1246:
	ds_read_b128 v[122:125], v196
	ds_read_b128 v[126:129], v196 offset:1024
	ds_read_b128 v[134:137], v196 offset:2048
	ds_read_b128 v[138:141], v196 offset:3072
	ds_read_b128 v[142:145], v197
	ds_read_b128 v[146:149], v197 offset:1024
	ds_read_b128 v[150:153], v197 offset:2048
	ds_read_b128 v[154:157], v197 offset:3072
	s_add_i32 s73, s64, 2
	s_add_u32 s62, s0, 0x100
	s_addc_u32 s63, s1, 0
	s_cmp_eq_u32 s64, 12
	s_cselect_b32 s64, s70, s71
	s_cselect_b32 s67, s55, s63
	s_cselect_b32 s66, s69, s62
	s_cselect_b32 s65, s53, s72
	v_lshl_add_u64 v[192:193], s[0:1], 0, v[180:181]
	s_add_i32 m0, s37, 0xc000
	ds_read_b128 v[162:165], v198
	ds_read_b128 v[166:169], v198 offset:1024
	ds_read_b128 v[188:191], v198 offset:2048
	ds_read_b128 v[202:205], v198 offset:3072
	ds_read_b128 v[206:209], v198 offset:4096
	ds_read_b128 v[210:213], v198 offset:5120
	ds_read_b128 v[214:217], v198 offset:6144
	ds_read_b128 v[218:221], v198 offset:7168
	global_load_lds_dwordx4 v[192:193], off
	v_lshl_add_u64 v[192:193], s[0:1], 0, v[182:183]
	s_add_i32 m0, s37, 0xe000
	s_nop 0
	global_load_lds_dwordx4 v[192:193], off
	s_cmp_lg_u32 s73, 0
	s_cbranch_scc0 .Lqx16
	s_waitcnt vmcnt(8)
.Lre16:
	s_waitcnt lgkmcnt(0)
	s_barrier
	s_setprio 1
	s_waitcnt lgkmcnt(0)
	v_mfma_f32_16x16x32_bf16 v[118:121], v[122:125], v[162:165], v[118:121]
	v_mfma_f32_16x16x32_bf16 v[114:117], v[134:137], v[162:165], v[114:117]
	v_mfma_f32_16x16x32_bf16 v[102:105], v[122:125], v[188:191], v[102:105]
	v_mfma_f32_16x16x32_bf16 v[98:101], v[134:137], v[188:191], v[98:101]
	v_mfma_f32_16x16x32_bf16 v[86:89], v[122:125], v[206:209], v[86:89]
	v_mfma_f32_16x16x32_bf16 v[82:85], v[134:137], v[206:209], v[82:85]
	v_mfma_f32_16x16x32_bf16 v[70:73], v[122:125], v[214:217], v[70:73]
	v_mfma_f32_16x16x32_bf16 v[66:69], v[134:137], v[214:217], v[66:69]
	v_mfma_f32_16x16x32_bf16 v[118:121], v[126:129], v[166:169], v[118:121]
	v_mfma_f32_16x16x32_bf16 v[114:117], v[138:141], v[166:169], v[114:117]
	v_mfma_f32_16x16x32_bf16 v[102:105], v[126:129], v[202:205], v[102:105]
	v_mfma_f32_16x16x32_bf16 v[98:101], v[138:141], v[202:205], v[98:101]
	v_mfma_f32_16x16x32_bf16 v[86:89], v[126:129], v[210:213], v[86:89]
	v_mfma_f32_16x16x32_bf16 v[82:85], v[138:141], v[210:213], v[82:85]
	v_mfma_f32_16x16x32_bf16 v[70:73], v[126:129], v[218:221], v[70:73]
	v_mfma_f32_16x16x32_bf16 v[66:69], v[138:141], v[218:221], v[66:69]
	s_setprio 0
	s_setprio 1
	v_mfma_f32_16x16x32_bf16 v[158:161], v[142:145], v[162:165], v[158:161]
	v_mfma_f32_16x16x32_bf16 v[130:133], v[150:153], v[162:165], v[130:133]
	v_mfma_f32_16x16x32_bf16 v[110:113], v[142:145], v[188:191], v[110:113]
	v_mfma_f32_16x16x32_bf16 v[106:109], v[150:153], v[188:191], v[106:109]
	v_mfma_f32_16x16x32_bf16 v[94:97], v[142:145], v[206:209], v[94:97]
	v_mfma_f32_16x16x32_bf16 v[90:93], v[150:153], v[206:209], v[90:93]
	v_mfma_f32_16x16x32_bf16 v[78:81], v[142:145], v[214:217], v[78:81]
	v_mfma_f32_16x16x32_bf16 v[74:77], v[150:153], v[214:217], v[74:77]
	v_mfma_f32_16x16x32_bf16 v[158:161], v[146:149], v[166:169], v[158:161]
	v_mfma_f32_16x16x32_bf16 v[130:133], v[154:157], v[166:169], v[130:133]
	v_mfma_f32_16x16x32_bf16 v[110:113], v[146:149], v[202:205], v[110:113]
	v_mfma_f32_16x16x32_bf16 v[106:109], v[154:157], v[202:205], v[106:109]
	v_mfma_f32_16x16x32_bf16 v[94:97], v[146:149], v[210:213], v[94:97]
	v_mfma_f32_16x16x32_bf16 v[90:93], v[154:157], v[210:213], v[90:93]
	v_mfma_f32_16x16x32_bf16 v[78:81], v[146:149], v[218:221], v[78:81]
	v_mfma_f32_16x16x32_bf16 v[74:77], v[154:157], v[218:221], v[74:77]
	s_setprio 0
	s_barrier
	s_add_i32 s0, s49, s34
	v_lshl_add_u64 v[192:193], s[64:65], 0, v[174:175]
	s_mov_b32 m0, s0
	ds_read_b128 v[162:165], v198 offset:16384
	ds_read_b128 v[166:169], v198 offset:17408
	ds_read_b128 v[188:191], v198 offset:18432
	ds_read_b128 v[202:205], v198 offset:19456
	ds_read_b128 v[206:209], v198 offset:20480
	ds_read_b128 v[210:213], v198 offset:21504
	ds_read_b128 v[214:217], v198 offset:22528
	ds_read_b128 v[218:221], v198 offset:23552
	global_load_lds_dwordx4 v[192:193], off
	s_add_i32 m0, s0, 0x2000
	s_add_u32 s0, s64, 0x40000
	v_lshl_add_u64 v[222:223], s[64:65], 0, v[170:171]
	s_addc_u32 s1, s65, 0
	s_add_i32 s74, s50, s34
	global_load_lds_dwordx4 v[222:223], off
	v_lshl_add_u64 v[224:225], s[0:1], 0, v[174:175]
	s_mov_b32 m0, s74
	v_lshl_add_u64 v[226:227], s[66:67], 0, v[172:173]
	global_load_lds_dwordx4 v[224:225], off
	v_lshl_add_u64 v[224:225], s[0:1], 0, v[170:171]
	s_add_i32 m0, s74, 0x2000
	s_nop 0
	global_load_lds_dwordx4 v[224:225], off
	v_lshl_add_u64 v[224:225], s[66:67], 0, v[176:177]
	s_mov_b32 m0, s37
	s_nop 0
	global_load_lds_dwordx4 v[224:225], off
	s_mov_b32 m0, s38
	s_nop 0
	global_load_lds_dwordx4 v[226:227], off
	s_cmp_lg_u32 s73, 0
	s_cbranch_scc0 .Lqx17
	s_waitcnt vmcnt(8)

.Lqx17:
	s_cmp_eq_u32 s61, 0
	s_cbranch_scc1 .Lqy17
	s_waitcnt vmcnt(24)
	s_branch .Lre17

; #define PG8_STAGE(bufoff, gbase, voff) do { _Pragma("unroll") for (int _i = 0; _i < 2; ++_i) \
;         __builtin_amdgcn_global_load_lds((const unsigned*)((const char*)(gbase) + (voff)[_i]), (LAS unsigned*)(lds + (bufoff) + ldsw + _i * 8192), 16, 0, 0); } while (0)
; #define PG8_LDA(dst, b, h) do { _Pragma("unroll") for (int m = 0; m < 4; ++m) _Pragma("unroll") for (int k = 0; k < 2; ++k) dst[m][k] = *(const LAS bf16x8*)(lds + PG8_SA(b, h) + aoff + m * 2048 + k * 1024); } while (0)
; #define PG8_LDB(dst, b, h) do { _Pragma("unroll") for (int n = 0; n < 2; ++n) _Pragma("unroll") for (int k = 0; k < 2; ++k) dst[n][k] = *(const LAS bf16x8*)(lds + PG8_SB(b, h) + boff + n * 2048 + k * 1024); } while (0)
; #define PG8_MMA(ai, bj, At, Bt) do { __builtin_amdgcn_s_setprio(1); _Pragma("unroll") for (int m = 0; m < 4; ++m) _Pragma("unroll") for (int n = 0; n < 2; ++n) _Pragma("unroll") for (int k = 0; k < 2; ++k) \
;         acc[ai][bj][m][n] = __builtin_amdgcn_mfma_f32_16x16x32_bf16(Bt[n][k], At[m][k], acc[ai][bj][m][n], 0, 0, 0); __builtin_amdgcn_s_setprio(0); } while (0)
; #define PG8_WAIT_L(n) asm volatile("s_waitcnt lgkmcnt(" #n ")" ::: "memory")
; #define PG8_BAR __builtin_amdgcn_s_barrier()
; #define PG8_FLAG(v) do { } while (0)
; #define PG8_SCHED __builtin_amdgcn_sched_barrier(0)
; template <class Epi, class Sched, bool APERM, bool ABLK = false, bool RELAX = true>
; __device__ __forceinline__ void gemm_phase(LAS unsigned char* lds, const Gemm g, const Sched& S, const Epi& E) {
;     ...
;             const bool last = (t == nt - 2);
;             const char* a1 = cA + (size_t)(t + 1) * kstepA;
;             const char* a2 = last ? nA : cA + (size_t)(t + 2) * kstepA; const char* b2 = last ? nB : cB + (size_t)(t + 2) * kstep;
;             const char* a3 = a2 + kstepA; const char* b3 = b2 + kstep;
;             PG8_LDB(B0, 0, 0); PG8_LDB(B1, 0, 1); PG8_SCHED; PG8_LDA(At, 0, 0); PG8_STAGE(PG8_SA(1, 1), a1 + hstepA, voffA);
;             PG8_WAIT_V8R; PG8_WAIT_L(0); PG8_BAR; PG8_MMA(0, 0, At, B0); PG8_MMA(0, 1, At, B1); PG8_BAR; PG8_SCHED;
;             PG8_LDA(At, 0, 1); PG8_STAGE(PG8_SB(0, 0), b2, voffB); PG8_STAGE(PG8_SB(0, 1), b2 + hstepB, voffB); PG8_STAGE(PG8_SA(0, 0), a2, voffA);
;             PG8_WAIT_V8R; PG8_FLAG(0u); PG8_WAIT_L(0); PG8_BAR; PG8_MMA(1, 0, At, B0); PG8_MMA(1, 1, At, B1); PG8_BAR; PG8_SCHED;
.LBB0_1409:
	ds_read_b128 v[134:137], v179
	ds_read_b128 v[154:157], v179 offset:1024
	ds_read_b128 v[158:161], v179 offset:2048
	ds_read_b128 v[162:165], v179 offset:3072
	ds_read_b128 v[166:169], v180
	ds_read_b128 v[172:175], v180 offset:1024
	ds_read_b128 v[182:185], v180 offset:2048
	ds_read_b128 v[186:189], v180 offset:3072
	s_add_i32 s64, s64, 2
	s_add_u32 s54, s52, s4
	s_addc_u32 s55, s53, s5
	s_add_u32 s54, s54, 0x900000
	s_addc_u32 s55, s55, 0
	s_cmp_eq_u32 s4, 0xbd00000
	s_cselect_b32 s58, s61, s54
	s_cselect_b32 s59, s13, s55
	s_cselect_b32 s56, s14, s62
	s_cselect_b32 s57, s15, s63
	s_add_u32 s54, s58, 0x480000
	s_addc_u32 s55, s59, 0
	v_lshl_add_u64 v[176:177], v[130:131], 0, s[4:5]
	s_add_i32 m0, s35, 0xc000
	ds_read_b128 v[190:193], v181
	ds_read_b128 v[194:197], v181 offset:1024
	ds_read_b128 v[198:201], v181 offset:2048
	ds_read_b128 v[202:205], v181 offset:3072
	ds_read_b128 v[206:209], v181 offset:4096
	ds_read_b128 v[210:213], v181 offset:5120
	ds_read_b128 v[214:217], v181 offset:6144
	ds_read_b128 v[218:221], v181 offset:7168
	global_load_lds_dwordx4 v[176:177], off
	v_lshl_add_u64 v[176:177], v[132:133], 0, s[4:5]
	s_add_i32 m0, s35, 0xe000
	s_nop 0
	global_load_lds_dwordx4 v[176:177], off
	s_cmp_lg_u32 s64, 0
	s_cbranch_scc0 .Lqx18
	s_waitcnt vmcnt(8)
.Lre18:
	s_waitcnt lgkmcnt(0)
	s_barrier
	s_setprio 1
	s_waitcnt lgkmcnt(0)
	v_mfma_f32_16x16x32_bf16 v[126:129], v[134:137], v[190:193], v[126:129]
	v_mfma_f32_16x16x32_bf16 v[122:125], v[158:161], v[190:193], v[122:125]
	v_mfma_f32_16x16x32_bf16 v[118:121], v[134:137], v[198:201], v[118:121]
	v_mfma_f32_16x16x32_bf16 v[114:117], v[158:161], v[198:201], v[114:117]
	v_mfma_f32_16x16x32_bf16 v[110:113], v[134:137], v[206:209], v[110:113]
	v_mfma_f32_16x16x32_bf16 v[106:109], v[158:161], v[206:209], v[106:109]
	v_mfma_f32_16x16x32_bf16 v[102:105], v[134:137], v[214:217], v[102:105]
	v_mfma_f32_16x16x32_bf16 v[98:101], v[158:161], v[214:217], v[98:101]
	v_mfma_f32_16x16x32_bf16 v[126:129], v[154:157], v[194:197], v[126:129]
	v_mfma_f32_16x16x32_bf16 v[122:125], v[162:165], v[194:197], v[122:125]
	v_mfma_f32_16x16x32_bf16 v[118:121], v[154:157], v[202:205], v[118:121]
	v_mfma_f32_16x16x32_bf16 v[114:117], v[162:165], v[202:205], v[114:117]
	v_mfma_f32_16x16x32_bf16 v[110:113], v[154:157], v[210:213], v[110:113]
	v_mfma_f32_16x16x32_bf16 v[106:109], v[162:165], v[210:213], v[106:109]
	v_mfma_f32_16x16x32_bf16 v[102:105], v[154:157], v[218:221], v[102:105]
	v_mfma_f32_16x16x32_bf16 v[98:101], v[162:165], v[218:221], v[98:101]
	s_setprio 0
	s_setprio 1
	v_mfma_f32_16x16x32_bf16 v[66:69], v[166:169], v[190:193], v[66:69]
	v_mfma_f32_16x16x32_bf16 v[58:61], v[182:185], v[190:193], v[58:61]
	v_mfma_f32_16x16x32_bf16 v[54:57], v[166:169], v[198:201], v[54:57]
	v_mfma_f32_16x16x32_bf16 v[50:53], v[182:185], v[198:201], v[50:53]
	v_mfma_f32_16x16x32_bf16 v[46:49], v[166:169], v[206:209], v[46:49]
	v_mfma_f32_16x16x32_bf16 v[42:45], v[182:185], v[206:209], v[42:45]
	v_mfma_f32_16x16x32_bf16 v[38:41], v[166:169], v[214:217], v[38:41]
	v_mfma_f32_16x16x32_bf16 v[34:37], v[182:185], v[214:217], v[34:37]
	v_mfma_f32_16x16x32_bf16 v[66:69], v[172:175], v[194:197], v[66:69]
	v_mfma_f32_16x16x32_bf16 v[58:61], v[186:189], v[194:197], v[58:61]
	v_mfma_f32_16x16x32_bf16 v[54:57], v[172:175], v[202:205], v[54:57]
	v_mfma_f32_16x16x32_bf16 v[50:53], v[186:189], v[202:205], v[50:53]
	v_mfma_f32_16x16x32_bf16 v[46:49], v[172:175], v[210:213], v[46:49]
	v_mfma_f32_16x16x32_bf16 v[42:45], v[186:189], v[210:213], v[42:45]
	v_mfma_f32_16x16x32_bf16 v[38:41], v[172:175], v[218:221], v[38:41]
	v_mfma_f32_16x16x32_bf16 v[34:37], v[186:189], v[218:221], v[34:37]
	s_setprio 0
	s_barrier
	s_add_i32 s65, s48, s34
	v_lshl_add_u64 v[176:177], s[56:57], 0, v[140:141]
	s_mov_b32 m0, s65
	ds_read_b128 v[190:193], v181 offset:16384
	ds_read_b128 v[194:197], v181 offset:17408
	ds_read_b128 v[198:201], v181 offset:18432
	ds_read_b128 v[202:205], v181 offset:19456
	ds_read_b128 v[206:209], v181 offset:20480
	ds_read_b128 v[210:213], v181 offset:21504
	ds_read_b128 v[214:217], v181 offset:22528
	ds_read_b128 v[218:221], v181 offset:23552
	global_load_lds_dwordx4 v[176:177], off
	s_add_i32 m0, s65, 0x2000
	s_add_u32 s66, s56, 0xb0000
	v_lshl_add_u64 v[222:223], s[56:57], 0, v[144:145]
	s_addc_u32 s67, s57, 0
	s_add_i32 s65, s49, s34
	global_load_lds_dwordx4 v[222:223], off
	v_lshl_add_u64 v[224:225], s[66:67], 0, v[140:141]
	s_mov_b32 m0, s65
	s_nop 0
	global_load_lds_dwordx4 v[224:225], off
	v_lshl_add_u64 v[224:225], s[66:67], 0, v[144:145]
	s_add_i32 m0, s65, 0x2000
	s_nop 0
	global_load_lds_dwordx4 v[224:225], off
	v_lshl_add_u64 v[224:225], s[58:59], 0, v[138:139]
	s_mov_b32 m0, s35
	s_nop 0
	global_load_lds_dwordx4 v[224:225], off
	v_lshl_add_u64 v[224:225], s[58:59], 0, v[142:143]
	s_mov_b32 m0, s36
	s_nop 0
	global_load_lds_dwordx4 v[224:225], off
	s_cmp_lg_u32 s64, 0
	s_cbranch_scc0 .Lqx19
	s_waitcnt vmcnt(8)

.Lqx19:
	s_cmp_eq_u32 s19, 0
	s_cbranch_scc1 .Lqy19
	s_waitcnt vmcnt(24)
	s_branch .Lre19

; #define PG8_STAGE(bufoff, gbase, voff) do { _Pragma("unroll") for (int _i = 0; _i < 2; ++_i) \
;         __builtin_amdgcn_global_load_lds((const unsigned*)((const char*)(gbase) + (voff)[_i]), (LAS unsigned*)(lds + (bufoff) + ldsw + _i * 8192), 16, 0, 0); } while (0)
; #define PG8_LDA(dst, b, h) do { _Pragma("unroll") for (int m = 0; m < 4; ++m) _Pragma("unroll") for (int k = 0; k < 2; ++k) dst[m][k] = *(const LAS bf16x8*)(lds + PG8_SA(b, h) + aoff + m * 2048 + k * 1024); } while (0)
; #define PG8_LDB(dst, b, h) do { _Pragma("unroll") for (int n = 0; n < 2; ++n) _Pragma("unroll") for (int k = 0; k < 2; ++k) dst[n][k] = *(const LAS bf16x8*)(lds + PG8_SB(b, h) + boff + n * 2048 + k * 1024); } while (0)
; #define PG8_MMA(ai, bj, At, Bt) do { __builtin_amdgcn_s_setprio(1); _Pragma("unroll") for (int m = 0; m < 4; ++m) _Pragma("unroll") for (int n = 0; n < 2; ++n) _Pragma("unroll") for (int k = 0; k < 2; ++k) \
;         acc[ai][bj][m][n] = __builtin_amdgcn_mfma_f32_16x16x32_bf16(Bt[n][k], At[m][k], acc[ai][bj][m][n], 0, 0, 0); __builtin_amdgcn_s_setprio(0); } while (0)
; #define PG8_WAIT_L(n) asm volatile("s_waitcnt lgkmcnt(" #n ")" ::: "memory")
; #define PG8_BAR __builtin_amdgcn_s_barrier()
; #define PG8_FLAG(v) do { } while (0)
; #define PG8_SCHED __builtin_amdgcn_sched_barrier(0)
; template <class Epi, class Sched, bool APERM, bool ABLK = false, bool RELAX = true>
; __device__ __forceinline__ void gemm_phase(LAS unsigned char* lds, const Gemm g, const Sched& S, const Epi& E) {
;     ...
;             const bool last = (t == nt - 2);
;             const char* a1 = cA + (size_t)(t + 1) * kstepA;
;             const char* a2 = last ? nA : cA + (size_t)(t + 2) * kstepA; const char* b2 = last ? nB : cB + (size_t)(t + 2) * kstep;
;             const char* a3 = a2 + kstepA; const char* b3 = b2 + kstep;
;             PG8_LDB(B0, 0, 0); PG8_LDB(B1, 0, 1); PG8_SCHED; PG8_LDA(At, 0, 0); PG8_STAGE(PG8_SA(1, 1), a1 + hstepA, voffA);
;             PG8_WAIT_V8R; PG8_WAIT_L(0); PG8_BAR; PG8_MMA(0, 0, At, B0); PG8_MMA(0, 1, At, B1); PG8_BAR; PG8_SCHED;
;             PG8_LDA(At, 0, 1); PG8_STAGE(PG8_SB(0, 0), b2, voffB); PG8_STAGE(PG8_SB(0, 1), b2 + hstepB, voffB); PG8_STAGE(PG8_SA(0, 0), a2, voffA);
;             PG8_WAIT_V8R; PG8_FLAG(0u); PG8_WAIT_L(0); PG8_BAR; PG8_MMA(1, 0, At, B0); PG8_MMA(1, 1, At, B1); PG8_BAR; PG8_SCHED;
.LBB0_1490:
	ds_read_b128 v[148:151], v143
	ds_read_b128 v[152:155], v143 offset:1024
	ds_read_b128 v[156:159], v143 offset:2048
	ds_read_b128 v[160:163], v143 offset:3072
	ds_read_b128 v[164:167], v144
	ds_read_b128 v[172:175], v144 offset:1024
	ds_read_b128 v[176:179], v144 offset:2048
	ds_read_b128 v[180:183], v144 offset:3072
	s_add_i32 s49, s10, 2
	s_add_u32 s11, s26, s37
	s_addc_u32 s12, s27, s38
	s_add_u32 s13, s26, s35
	s_addc_u32 s50, s27, s36
	s_cmp_eq_u32 s10, 18
	s_cselect_b32 s14, s4, s11
	s_cselect_b32 s15, s5, s12
	s_cselect_b32 s12, s0, s13
	s_cselect_b32 s13, s1, s50
	s_add_u32 s10, s14, 0x480000
	s_addc_u32 s11, s15, 0
	s_mov_b32 m0, s39
	v_lshl_add_u64 v[168:169], s[26:27], 0, v[138:139]
	ds_read_b128 v[184:187], v145
	ds_read_b128 v[188:191], v145 offset:1024
	ds_read_b128 v[192:195], v145 offset:2048
	ds_read_b128 v[196:199], v145 offset:3072
	ds_read_b128 v[200:203], v145 offset:4096
	ds_read_b128 v[204:207], v145 offset:5120
	ds_read_b128 v[208:211], v145 offset:6144
	ds_read_b128 v[212:215], v145 offset:7168
	global_load_lds_dwordx4 v[168:169], off
	v_lshl_add_u64 v[168:169], s[26:27], 0, v[140:141]
	s_mov_b32 m0, s40
	s_nop 0
	global_load_lds_dwordx4 v[168:169], off
	s_cmp_lg_u32 s49, 0
	s_cbranch_scc0 .Lqx20
	s_waitcnt vmcnt(8)
.Lre20:
	s_waitcnt lgkmcnt(0)
	s_barrier
	s_setprio 1
	s_waitcnt lgkmcnt(0)
	v_mfma_f32_16x16x32_bf16 v[126:129], v[148:151], v[184:187], v[126:129]
	v_mfma_f32_16x16x32_bf16 v[122:125], v[156:159], v[184:187], v[122:125]
	v_mfma_f32_16x16x32_bf16 v[118:121], v[148:151], v[192:195], v[118:121]
	v_mfma_f32_16x16x32_bf16 v[114:117], v[156:159], v[192:195], v[114:117]
	v_mfma_f32_16x16x32_bf16 v[110:113], v[148:151], v[200:203], v[110:113]
	v_mfma_f32_16x16x32_bf16 v[106:109], v[156:159], v[200:203], v[106:109]
	v_mfma_f32_16x16x32_bf16 v[102:105], v[148:151], v[208:211], v[102:105]
	v_mfma_f32_16x16x32_bf16 v[98:101], v[156:159], v[208:211], v[98:101]
	v_mfma_f32_16x16x32_bf16 v[126:129], v[152:155], v[188:191], v[126:129]
	v_mfma_f32_16x16x32_bf16 v[122:125], v[160:163], v[188:191], v[122:125]
	v_mfma_f32_16x16x32_bf16 v[118:121], v[152:155], v[196:199], v[118:121]
	v_mfma_f32_16x16x32_bf16 v[114:117], v[160:163], v[196:199], v[114:117]
	v_mfma_f32_16x16x32_bf16 v[110:113], v[152:155], v[204:207], v[110:113]
	v_mfma_f32_16x16x32_bf16 v[106:109], v[160:163], v[204:207], v[106:109]
	v_mfma_f32_16x16x32_bf16 v[102:105], v[152:155], v[212:215], v[102:105]
	v_mfma_f32_16x16x32_bf16 v[98:101], v[160:163], v[212:215], v[98:101]
	s_setprio 0
	s_setprio 1
	v_mfma_f32_16x16x32_bf16 v[66:69], v[164:167], v[184:187], v[66:69]
	v_mfma_f32_16x16x32_bf16 v[58:61], v[176:179], v[184:187], v[58:61]
	v_mfma_f32_16x16x32_bf16 v[54:57], v[164:167], v[192:195], v[54:57]
	v_mfma_f32_16x16x32_bf16 v[50:53], v[176:179], v[192:195], v[50:53]
	v_mfma_f32_16x16x32_bf16 v[46:49], v[164:167], v[200:203], v[46:49]
	v_mfma_f32_16x16x32_bf16 v[42:45], v[176:179], v[200:203], v[42:45]
	v_mfma_f32_16x16x32_bf16 v[38:41], v[164:167], v[208:211], v[38:41]
	v_mfma_f32_16x16x32_bf16 v[34:37], v[176:179], v[208:211], v[34:37]
	v_mfma_f32_16x16x32_bf16 v[66:69], v[172:175], v[188:191], v[66:69]
	v_mfma_f32_16x16x32_bf16 v[58:61], v[180:183], v[188:191], v[58:61]
	v_mfma_f32_16x16x32_bf16 v[54:57], v[172:175], v[196:199], v[54:57]
	v_mfma_f32_16x16x32_bf16 v[50:53], v[180:183], v[196:199], v[50:53]
	v_mfma_f32_16x16x32_bf16 v[46:49], v[172:175], v[204:207], v[46:49]
	v_mfma_f32_16x16x32_bf16 v[42:45], v[180:183], v[204:207], v[42:45]
	v_mfma_f32_16x16x32_bf16 v[38:41], v[172:175], v[212:215], v[38:41]
	v_mfma_f32_16x16x32_bf16 v[34:37], v[180:183], v[212:215], v[34:37]
	s_setprio 0
	s_barrier
	s_mov_b32 m0, s41
	v_lshl_add_u64 v[168:169], s[12:13], 0, v[132:133]
	s_add_u32 s50, s12, 0xb0000
	ds_read_b128 v[184:187], v145 offset:16384
	ds_read_b128 v[188:191], v145 offset:17408
	ds_read_b128 v[192:195], v145 offset:18432
	ds_read_b128 v[196:199], v145 offset:19456
	ds_read_b128 v[200:203], v145 offset:20480
	ds_read_b128 v[204:207], v145 offset:21504
	ds_read_b128 v[208:211], v145 offset:22528
	ds_read_b128 v[212:215], v145 offset:23552
	global_load_lds_dwordx4 v[168:169], off
	v_lshl_add_u64 v[216:217], s[12:13], 0, v[136:137]
	s_mov_b32 m0, s42
	s_addc_u32 s51, s13, 0
	global_load_lds_dwordx4 v[216:217], off
	v_lshl_add_u64 v[218:219], s[50:51], 0, v[132:133]
	s_mov_b32 m0, s43
	s_nop 0
	global_load_lds_dwordx4 v[218:219], off
	v_lshl_add_u64 v[218:219], s[50:51], 0, v[136:137]
	s_mov_b32 m0, s44
	s_nop 0
	global_load_lds_dwordx4 v[218:219], off
	v_lshl_add_u64 v[218:219], s[14:15], 0, v[130:131]
	s_mov_b32 m0, s21
	s_nop 0
	global_load_lds_dwordx4 v[218:219], off
	v_lshl_add_u64 v[218:219], s[14:15], 0, v[134:135]
	s_mov_b32 m0, s22
	s_nop 0
	global_load_lds_dwordx4 v[218:219], off
	s_cmp_lg_u32 s49, 0
	s_cbranch_scc0 .Lqx21
	s_waitcnt vmcnt(8)

.Lqx21:
	s_cmp_eq_u32 s29, 0
	s_cbranch_scc1 .Lqy21
	s_waitcnt vmcnt(24)
	s_branch .Lre21

; #define PG8_STAGE(bufoff, gbase, voff) do { _Pragma("unroll") for (int _i = 0; _i < 2; ++_i) \
;         __builtin_amdgcn_global_load_lds((const unsigned*)((const char*)(gbase) + (voff)[_i]), (LAS unsigned*)(lds + (bufoff) + ldsw + _i * 8192), 16, 0, 0); } while (0)
; #define PG8_LDA(dst, b, h) do { _Pragma("unroll") for (int m = 0; m < 4; ++m) _Pragma("unroll") for (int k = 0; k < 2; ++k) dst[m][k] = *(const LAS bf16x8*)(lds + PG8_SA(b, h) + aoff + m * 2048 + k * 1024); } while (0)
; #define PG8_LDB(dst, b, h) do { _Pragma("unroll") for (int n = 0; n < 2; ++n) _Pragma("unroll") for (int k = 0; k < 2; ++k) dst[n][k] = *(const LAS bf16x8*)(lds + PG8_SB(b, h) + boff + n * 2048 + k * 1024); } while (0)
; #define PG8_MMA(ai, bj, At, Bt) do { __builtin_amdgcn_s_setprio(1); _Pragma("unroll") for (int m = 0; m < 4; ++m) _Pragma("unroll") for (int n = 0; n < 2; ++n) _Pragma("unroll") for (int k = 0; k < 2; ++k) \
;         acc[ai][bj][m][n] = __builtin_amdgcn_mfma_f32_16x16x32_bf16(Bt[n][k], At[m][k], acc[ai][bj][m][n], 0, 0, 0); __builtin_amdgcn_s_setprio(0); } while (0)
; #define PG8_WAIT_L(n) asm volatile("s_waitcnt lgkmcnt(" #n ")" ::: "memory")
; #define PG8_BAR __builtin_amdgcn_s_barrier()
; #define PG8_FLAG(v) do { } while (0)
; #define PG8_SCHED __builtin_amdgcn_sched_barrier(0)
; template <class Epi, class Sched, bool APERM, bool ABLK = false, bool RELAX = true>
; __device__ __forceinline__ void gemm_phase(LAS unsigned char* lds, const Gemm g, const Sched& S, const Epi& E) {
;     ...
;             const bool last = (t == nt - 2);
;             const char* a1 = cA + (size_t)(t + 1) * kstepA;
;             const char* a2 = last ? nA : cA + (size_t)(t + 2) * kstepA; const char* b2 = last ? nB : cB + (size_t)(t + 2) * kstep;
;             const char* a3 = a2 + kstepA; const char* b3 = b2 + kstep;
;             PG8_LDB(B0, 0, 0); PG8_LDB(B1, 0, 1); PG8_SCHED; PG8_LDA(At, 0, 0); PG8_STAGE(PG8_SA(1, 1), a1 + hstepA, voffA);
;             PG8_WAIT_V8R; PG8_WAIT_L(0); PG8_BAR; PG8_MMA(0, 0, At, B0); PG8_MMA(0, 1, At, B1); PG8_BAR; PG8_SCHED;
;             PG8_LDA(At, 0, 1); PG8_STAGE(PG8_SB(0, 0), b2, voffB); PG8_STAGE(PG8_SB(0, 1), b2 + hstepB, voffB); PG8_STAGE(PG8_SA(0, 0), a2, voffA);
;             PG8_WAIT_V8R; PG8_FLAG(0u); PG8_WAIT_L(0); PG8_BAR; PG8_MMA(1, 0, At, B0); PG8_MMA(1, 1, At, B1); PG8_BAR; PG8_SCHED;
.LBB0_1660:
	ds_read_b128 v[98:101], v188
	ds_read_b128 v[134:137], v188 offset:1024
	ds_read_b128 v[138:141], v188 offset:2048
	ds_read_b128 v[156:159], v188 offset:3072
	ds_read_b128 v[160:163], v189
	ds_read_b128 v[164:167], v189 offset:1024
	ds_read_b128 v[172:175], v189 offset:2048
	ds_read_b128 v[176:179], v189 offset:3072
	s_add_i32 s75, s6, 2
	s_add_u32 s7, s4, 0xfffc0080
	s_addc_u32 s8, s5, -1
	s_cmp_eq_u32 s6, 12
	s_cselect_b32 s6, s72, s73
	s_cselect_b32 s9, s61, s8
	s_cselect_b32 s8, s71, s7
	s_cselect_b32 s7, s59, s74
	v_lshl_add_u64 v[168:169], s[4:5], 0, v[150:151]
	s_add_i32 m0, s35, 0xc000
	ds_read_b128 v[180:183], v190
	ds_read_b128 v[192:195], v190 offset:1024
	ds_read_b128 v[196:199], v190 offset:2048
	ds_read_b128 v[200:203], v190 offset:3072
	ds_read_b128 v[204:207], v190 offset:4096
	ds_read_b128 v[208:211], v190 offset:5120
	ds_read_b128 v[212:215], v190 offset:6144
	ds_read_b128 v[216:219], v190 offset:7168
	global_load_lds_dwordx4 v[168:169], off
	v_lshl_add_u64 v[168:169], s[4:5], 0, v[152:153]
	s_add_i32 m0, s35, 0xe000
	s_nop 0
	global_load_lds_dwordx4 v[168:169], off
	s_cmp_lg_u32 s75, 0
	s_cbranch_scc0 .Lqx22
	s_waitcnt vmcnt(8)
.Lre22:
	s_waitcnt lgkmcnt(0)
	s_barrier
	s_setprio 1
	s_waitcnt lgkmcnt(0)
	v_mfma_f32_16x16x32_bf16 v[126:129], v[98:101], v[180:183], v[126:129]
	v_mfma_f32_16x16x32_bf16 v[130:133], v[138:141], v[180:183], v[130:133]
	v_mfma_f32_16x16x32_bf16 v[110:113], v[98:101], v[196:199], v[110:113]
	v_mfma_f32_16x16x32_bf16 v[114:117], v[138:141], v[196:199], v[114:117]
	v_mfma_f32_16x16x32_bf16 v[90:93], v[98:101], v[204:207], v[90:93]
	v_mfma_f32_16x16x32_bf16 v[94:97], v[138:141], v[204:207], v[94:97]
	v_mfma_f32_16x16x32_bf16 v[74:77], v[98:101], v[212:215], v[74:77]
	v_mfma_f32_16x16x32_bf16 v[78:81], v[138:141], v[212:215], v[78:81]
	v_mfma_f32_16x16x32_bf16 v[126:129], v[134:137], v[192:195], v[126:129]
	v_mfma_f32_16x16x32_bf16 v[130:133], v[156:159], v[192:195], v[130:133]
	v_mfma_f32_16x16x32_bf16 v[110:113], v[134:137], v[200:203], v[110:113]
	v_mfma_f32_16x16x32_bf16 v[114:117], v[156:159], v[200:203], v[114:117]
	v_mfma_f32_16x16x32_bf16 v[90:93], v[134:137], v[208:211], v[90:93]
	v_mfma_f32_16x16x32_bf16 v[94:97], v[156:159], v[208:211], v[94:97]
	v_mfma_f32_16x16x32_bf16 v[74:77], v[134:137], v[216:219], v[74:77]
	v_mfma_f32_16x16x32_bf16 v[78:81], v[156:159], v[216:219], v[78:81]
	s_setprio 0
	s_setprio 1
	v_mfma_f32_16x16x32_bf16 v[118:121], v[160:163], v[180:183], v[118:121]
	v_mfma_f32_16x16x32_bf16 v[122:125], v[172:175], v[180:183], v[122:125]
	v_mfma_f32_16x16x32_bf16 v[102:105], v[160:163], v[196:199], v[102:105]
	v_mfma_f32_16x16x32_bf16 v[106:109], v[172:175], v[196:199], v[106:109]
	v_mfma_f32_16x16x32_bf16 v[82:85], v[160:163], v[204:207], v[82:85]
	v_mfma_f32_16x16x32_bf16 v[86:89], v[172:175], v[204:207], v[86:89]
	v_mfma_f32_16x16x32_bf16 v[66:69], v[160:163], v[212:215], v[66:69]
	v_mfma_f32_16x16x32_bf16 v[70:73], v[172:175], v[212:215], v[70:73]
	v_mfma_f32_16x16x32_bf16 v[118:121], v[164:167], v[192:195], v[118:121]
	v_mfma_f32_16x16x32_bf16 v[122:125], v[176:179], v[192:195], v[122:125]
	v_mfma_f32_16x16x32_bf16 v[102:105], v[164:167], v[200:203], v[102:105]
	v_mfma_f32_16x16x32_bf16 v[106:109], v[176:179], v[200:203], v[106:109]
	v_mfma_f32_16x16x32_bf16 v[82:85], v[164:167], v[208:211], v[82:85]
	v_mfma_f32_16x16x32_bf16 v[86:89], v[176:179], v[208:211], v[86:89]
	v_mfma_f32_16x16x32_bf16 v[66:69], v[164:167], v[216:219], v[66:69]
	v_mfma_f32_16x16x32_bf16 v[70:73], v[176:179], v[216:219], v[70:73]
	s_setprio 0
	s_barrier
	s_add_i32 s76, s51, s34
	v_lshl_add_u64 v[168:169], s[6:7], 0, v[144:145]
	s_mov_b32 m0, s76
	ds_read_b128 v[180:183], v190 offset:16384
	ds_read_b128 v[192:195], v190 offset:17408
	ds_read_b128 v[196:199], v190 offset:18432
	ds_read_b128 v[200:203], v190 offset:19456
	ds_read_b128 v[204:207], v190 offset:20480
	ds_read_b128 v[208:211], v190 offset:21504
	ds_read_b128 v[212:215], v190 offset:22528
	ds_read_b128 v[216:219], v190 offset:23552
	global_load_lds_dwordx4 v[168:169], off
	s_add_i32 m0, s76, 0x2000
	s_add_u32 s76, s6, 0x40000
	v_lshl_add_u64 v[184:185], s[6:7], 0, v[148:149]
	s_addc_u32 s77, s7, 0
	s_add_i32 s78, s53, s34
	global_load_lds_dwordx4 v[184:185], off
	v_lshl_add_u64 v[220:221], s[76:77], 0, v[144:145]
	s_mov_b32 m0, s78
	v_lshl_add_u64 v[222:223], s[8:9], 0, v[146:147]
	global_load_lds_dwordx4 v[220:221], off
	v_lshl_add_u64 v[220:221], s[76:77], 0, v[148:149]
	s_add_i32 m0, s78, 0x2000
	s_nop 0
	global_load_lds_dwordx4 v[220:221], off
	v_lshl_add_u64 v[220:221], s[8:9], 0, v[142:143]
	s_mov_b32 m0, s35
	s_nop 0
	global_load_lds_dwordx4 v[220:221], off
	s_mov_b32 m0, s36
	s_nop 0
	global_load_lds_dwordx4 v[222:223], off
	s_cmp_lg_u32 s75, 0
	s_cbranch_scc0 .Lqx23
	s_waitcnt vmcnt(8)

.Lqx23:
	s_cmp_eq_u32 s12, 0
	s_cbranch_scc1 .Lqy23
	s_waitcnt vmcnt(24)
	s_branch .Lre23

; #define PG8_STAGE(bufoff, gbase, voff) do { _Pragma("unroll") for (int _i = 0; _i < 2; ++_i) \
;         __builtin_amdgcn_global_load_lds((const unsigned*)((const char*)(gbase) + (voff)[_i]), (LAS unsigned*)(lds + (bufoff) + ldsw + _i * 8192), 16, 0, 0); } while (0)
; #define PG8_LDA(dst, b, h) do { _Pragma("unroll") for (int m = 0; m < 4; ++m) _Pragma("unroll") for (int k = 0; k < 2; ++k) dst[m][k] = *(const LAS bf16x8*)(lds + PG8_SA(b, h) + aoff + m * 2048 + k * 1024); } while (0)
; #define PG8_LDB(dst, b, h) do { _Pragma("unroll") for (int n = 0; n < 2; ++n) _Pragma("unroll") for (int k = 0; k < 2; ++k) dst[n][k] = *(const LAS bf16x8*)(lds + PG8_SB(b, h) + boff + n * 2048 + k * 1024); } while (0)
; #define PG8_MMA(ai, bj, At, Bt) do { __builtin_amdgcn_s_setprio(1); _Pragma("unroll") for (int m = 0; m < 4; ++m) _Pragma("unroll") for (int n = 0; n < 2; ++n) _Pragma("unroll") for (int k = 0; k < 2; ++k) \
;         acc[ai][bj][m][n] = __builtin_amdgcn_mfma_f32_16x16x32_bf16(Bt[n][k], At[m][k], acc[ai][bj][m][n], 0, 0, 0); __builtin_amdgcn_s_setprio(0); } while (0)
; #define PG8_WAIT_L(n) asm volatile("s_waitcnt lgkmcnt(" #n ")" ::: "memory")
; #define PG8_BAR __builtin_amdgcn_s_barrier()
; #define PG8_FLAG(v) do { } while (0)
; #define PG8_SCHED __builtin_amdgcn_sched_barrier(0)
; template <class Epi, class Sched, bool APERM, bool ABLK = false, bool RELAX = true>
; __device__ __forceinline__ void gemm_phase(LAS unsigned char* lds, const Gemm g, const Sched& S, const Epi& E) {
;     ...
;             const bool last = (t == nt - 2);
;             const char* a1 = cA + (size_t)(t + 1) * kstepA;
;             const char* a2 = last ? nA : cA + (size_t)(t + 2) * kstepA; const char* b2 = last ? nB : cB + (size_t)(t + 2) * kstep;
;             const char* a3 = a2 + kstepA; const char* b3 = b2 + kstep;
;             PG8_LDB(B0, 0, 0); PG8_LDB(B1, 0, 1); PG8_SCHED; PG8_LDA(At, 0, 0); PG8_STAGE(PG8_SA(1, 1), a1 + hstepA, voffA);
;             PG8_WAIT_V8R; PG8_WAIT_L(0); PG8_BAR; PG8_MMA(0, 0, At, B0); PG8_MMA(0, 1, At, B1); PG8_BAR; PG8_SCHED;
;             PG8_LDA(At, 0, 1); PG8_STAGE(PG8_SB(0, 0), b2, voffB); PG8_STAGE(PG8_SB(0, 1), b2 + hstepB, voffB); PG8_STAGE(PG8_SA(0, 0), a2, voffA);
;             PG8_WAIT_V8R; PG8_FLAG(0u); PG8_WAIT_L(0); PG8_BAR; PG8_MMA(1, 0, At, B0); PG8_MMA(1, 1, At, B1); PG8_BAR; PG8_SCHED;
.LBB0_2039:
	ds_read_b128 v[130:133], v179
	ds_read_b128 v[134:137], v179 offset:1024
	ds_read_b128 v[154:157], v179 offset:2048
	ds_read_b128 v[158:161], v179 offset:3072
	ds_read_b128 v[162:165], v180
	ds_read_b128 v[166:169], v180 offset:1024
	ds_read_b128 v[172:175], v180 offset:2048
	ds_read_b128 v[182:185], v180 offset:3072
	s_add_i32 s58, s22, 2
	s_add_u32 s23, s20, 0xfffc0080
	s_addc_u32 s36, s21, -1
	s_cmp_eq_u32 s22, 12
	s_cselect_b32 s22, s55, s56
	s_cselect_b32 s37, s13, s36
	s_cselect_b32 s36, s54, s23
	s_cselect_b32 s23, s11, s57
	v_lshl_add_u64 v[176:177], s[20:21], 0, v[146:147]
	s_add_i32 m0, s35, 0xc000
	ds_read_b128 v[186:189], v181
	ds_read_b128 v[190:193], v181 offset:1024
	ds_read_b128 v[194:197], v181 offset:2048
	ds_read_b128 v[198:201], v181 offset:3072
	ds_read_b128 v[202:205], v181 offset:4096
	ds_read_b128 v[206:209], v181 offset:5120
	ds_read_b128 v[210:213], v181 offset:6144
	ds_read_b128 v[214:217], v181 offset:7168
	global_load_lds_dwordx4 v[176:177], off
	v_lshl_add_u64 v[176:177], s[20:21], 0, v[148:149]
	s_add_i32 m0, s35, 0xe000
	s_nop 0
	global_load_lds_dwordx4 v[176:177], off
	s_cmp_lg_u32 s58, 0
	s_cbranch_scc0 .Lqx24
	s_waitcnt vmcnt(8)
.Lre24:
	s_waitcnt lgkmcnt(0)
	s_barrier
	s_setprio 1
	s_waitcnt lgkmcnt(0)
	v_mfma_f32_16x16x32_bf16 v[126:129], v[130:133], v[186:189], v[126:129]
	v_mfma_f32_16x16x32_bf16 v[122:125], v[154:157], v[186:189], v[122:125]
	v_mfma_f32_16x16x32_bf16 v[118:121], v[130:133], v[194:197], v[118:121]
	v_mfma_f32_16x16x32_bf16 v[114:117], v[154:157], v[194:197], v[114:117]
	v_mfma_f32_16x16x32_bf16 v[110:113], v[130:133], v[202:205], v[110:113]
	v_mfma_f32_16x16x32_bf16 v[106:109], v[154:157], v[202:205], v[106:109]
	v_mfma_f32_16x16x32_bf16 v[102:105], v[130:133], v[210:213], v[102:105]
	v_mfma_f32_16x16x32_bf16 v[98:101], v[154:157], v[210:213], v[98:101]
	v_mfma_f32_16x16x32_bf16 v[126:129], v[134:137], v[190:193], v[126:129]
	v_mfma_f32_16x16x32_bf16 v[122:125], v[158:161], v[190:193], v[122:125]
	v_mfma_f32_16x16x32_bf16 v[118:121], v[134:137], v[198:201], v[118:121]
	v_mfma_f32_16x16x32_bf16 v[114:117], v[158:161], v[198:201], v[114:117]
	v_mfma_f32_16x16x32_bf16 v[110:113], v[134:137], v[206:209], v[110:113]
	v_mfma_f32_16x16x32_bf16 v[106:109], v[158:161], v[206:209], v[106:109]
	v_mfma_f32_16x16x32_bf16 v[102:105], v[134:137], v[214:217], v[102:105]
	v_mfma_f32_16x16x32_bf16 v[98:101], v[158:161], v[214:217], v[98:101]
	s_setprio 0
	s_setprio 1
	v_mfma_f32_16x16x32_bf16 v[66:69], v[162:165], v[186:189], v[66:69]
	v_mfma_f32_16x16x32_bf16 v[58:61], v[172:175], v[186:189], v[58:61]
	v_mfma_f32_16x16x32_bf16 v[54:57], v[162:165], v[194:197], v[54:57]
	v_mfma_f32_16x16x32_bf16 v[50:53], v[172:175], v[194:197], v[50:53]
	v_mfma_f32_16x16x32_bf16 v[46:49], v[162:165], v[202:205], v[46:49]
	v_mfma_f32_16x16x32_bf16 v[42:45], v[172:175], v[202:205], v[42:45]
	v_mfma_f32_16x16x32_bf16 v[38:41], v[162:165], v[210:213], v[38:41]
	v_mfma_f32_16x16x32_bf16 v[34:37], v[172:175], v[210:213], v[34:37]
	v_mfma_f32_16x16x32_bf16 v[66:69], v[166:169], v[190:193], v[66:69]
	v_mfma_f32_16x16x32_bf16 v[58:61], v[182:185], v[190:193], v[58:61]
	v_mfma_f32_16x16x32_bf16 v[54:57], v[166:169], v[198:201], v[54:57]
	v_mfma_f32_16x16x32_bf16 v[50:53], v[182:185], v[198:201], v[50:53]
	v_mfma_f32_16x16x32_bf16 v[46:49], v[166:169], v[206:209], v[46:49]
	v_mfma_f32_16x16x32_bf16 v[42:45], v[182:185], v[206:209], v[42:45]
	v_mfma_f32_16x16x32_bf16 v[38:41], v[166:169], v[214:217], v[38:41]
	v_mfma_f32_16x16x32_bf16 v[34:37], v[182:185], v[214:217], v[34:37]
	s_setprio 0
	s_barrier
	s_add_i32 s59, s50, s34
	v_lshl_add_u64 v[176:177], s[22:23], 0, v[140:141]
	s_mov_b32 m0, s59
	ds_read_b128 v[186:189], v181 offset:16384
	ds_read_b128 v[190:193], v181 offset:17408
	ds_read_b128 v[194:197], v181 offset:18432
	ds_read_b128 v[198:201], v181 offset:19456
	ds_read_b128 v[202:205], v181 offset:20480
	ds_read_b128 v[206:209], v181 offset:21504
	ds_read_b128 v[210:213], v181 offset:22528
	ds_read_b128 v[214:217], v181 offset:23552
	global_load_lds_dwordx4 v[176:177], off
	s_add_i32 m0, s59, 0x2000
	s_add_u32 s60, s22, 0x40000
	v_lshl_add_u64 v[218:219], s[22:23], 0, v[144:145]
	s_addc_u32 s61, s23, 0
	s_add_i32 s59, s51, s34
	global_load_lds_dwordx4 v[218:219], off
	v_lshl_add_u64 v[220:221], s[60:61], 0, v[140:141]
	s_mov_b32 m0, s59
	v_lshl_add_u64 v[222:223], s[36:37], 0, v[142:143]
	global_load_lds_dwordx4 v[220:221], off
	v_lshl_add_u64 v[220:221], s[60:61], 0, v[144:145]
	s_add_i32 m0, s59, 0x2000
	s_nop 0
	global_load_lds_dwordx4 v[220:221], off
	v_lshl_add_u64 v[220:221], s[36:37], 0, v[138:139]
	s_mov_b32 m0, s35
	s_nop 0
	global_load_lds_dwordx4 v[220:221], off
	s_mov_b32 m0, s38
	s_nop 0
	global_load_lds_dwordx4 v[222:223], off
	s_cmp_lg_u32 s58, 0
	s_cbranch_scc0 .Lqx25
	s_waitcnt vmcnt(8)

; #define PG8_STAGE(bufoff, gbase, voff) do { _Pragma("unroll") for (int _i = 0; _i < 2; ++_i) \
;         __builtin_amdgcn_global_load_lds((const unsigned*)((const char*)(gbase) + (voff)[_i]), (LAS unsigned*)(lds + (bufoff) + ldsw + _i * 8192), 16, 0, 0); } while (0)
; #define PG8_LDA(dst, b, h) do { _Pragma("unroll") for (int m = 0; m < 4; ++m) _Pragma("unroll") for (int k = 0; k < 2; ++k) dst[m][k] = *(const LAS bf16x8*)(lds + PG8_SA(b, h) + aoff + m * 2048 + k * 1024); } while (0)
; #define PG8_LDB(dst, b, h) do { _Pragma("unroll") for (int n = 0; n < 2; ++n) _Pragma("unroll") for (int k = 0; k < 2; ++k) dst[n][k] = *(const LAS bf16x8*)(lds + PG8_SB(b, h) + boff + n * 2048 + k * 1024); } while (0)
; #define PG8_MMA(ai, bj, At, Bt) do { __builtin_amdgcn_s_setprio(1); _Pragma("unroll") for (int m = 0; m < 4; ++m) _Pragma("unroll") for (int n = 0; n < 2; ++n) _Pragma("unroll") for (int k = 0; k < 2; ++k) \
;         acc[ai][bj][m][n] = __builtin_amdgcn_mfma_f32_16x16x32_bf16(Bt[n][k], At[m][k], acc[ai][bj][m][n], 0, 0, 0); __builtin_amdgcn_s_setprio(0); } while (0)
; #define PG8_WAIT_L(n) asm volatile("s_waitcnt lgkmcnt(" #n ")" ::: "memory")
; #define PG8_BAR __builtin_amdgcn_s_barrier()
; #define PG8_FLAG(v) do { } while (0)
; #define PG8_SCHED __builtin_amdgcn_sched_barrier(0)
; template <class Epi, class Sched, bool APERM, bool ABLK = false, bool RELAX = true>
; __device__ __forceinline__ void gemm_phase(LAS unsigned char* lds, const Gemm g, const Sched& S, const Epi& E) {
;     ...
;             const bool last = (t == nt - 2);
;             const char* a1 = cA + (size_t)(t + 1) * kstepA;
;             const char* a2 = last ? nA : cA + (size_t)(t + 2) * kstepA; const char* b2 = last ? nB : cB + (size_t)(t + 2) * kstep;
;             const char* a3 = a2 + kstepA; const char* b3 = b2 + kstep;
;             PG8_LDB(B0, 0, 0); PG8_LDB(B1, 0, 1); PG8_SCHED; PG8_LDA(At, 0, 0); PG8_STAGE(PG8_SA(1, 1), a1 + hstepA, voffA);
;             PG8_WAIT_V8R; PG8_WAIT_L(0); PG8_BAR; PG8_MMA(0, 0, At, B0); PG8_MMA(0, 1, At, B1); PG8_BAR; PG8_SCHED;
;             PG8_LDA(At, 0, 1); PG8_STAGE(PG8_SB(0, 0), b2, voffB); PG8_STAGE(PG8_SB(0, 1), b2 + hstepB, voffB); PG8_STAGE(PG8_SA(0, 0), a2, voffA);
;             PG8_WAIT_V8R; PG8_FLAG(0u); PG8_WAIT_L(0); PG8_BAR; PG8_MMA(1, 0, At, B0); PG8_MMA(1, 1, At, B1); PG8_BAR; PG8_SCHED;
.LBB0_2173:
	ds_read_b128 v[122:125], v197
	ds_read_b128 v[126:129], v197 offset:1024
	ds_read_b128 v[134:137], v197 offset:2048
	ds_read_b128 v[138:141], v197 offset:3072
	ds_read_b128 v[142:145], v198
	ds_read_b128 v[146:149], v198 offset:1024
	ds_read_b128 v[150:153], v198 offset:2048
	ds_read_b128 v[154:157], v198 offset:3072
	s_add_i32 s69, s46, 2
	s_add_u32 s42, s0, 0x100
	s_addc_u32 s43, s1, 0
	s_cmp_eq_u32 s46, 12
	s_cselect_b32 s46, s66, s67
	s_cselect_b32 s49, s23, s43
	s_cselect_b32 s48, s65, s42
	s_cselect_b32 s47, s21, s68
	v_lshl_add_u64 v[194:195], s[0:1], 0, v[182:183]
	s_add_i32 m0, s45, 0xc000
	ds_read_b128 v[162:165], v199
	ds_read_b128 v[166:169], v199 offset:1024
	ds_read_b128 v[190:193], v199 offset:2048
	ds_read_b128 v[202:205], v199 offset:3072
	ds_read_b128 v[206:209], v199 offset:4096
	ds_read_b128 v[210:213], v199 offset:5120
	ds_read_b128 v[214:217], v199 offset:6144
	ds_read_b128 v[218:221], v199 offset:7168
	global_load_lds_dwordx4 v[194:195], off
	v_lshl_add_u64 v[194:195], s[0:1], 0, v[184:185]
	s_add_i32 m0, s45, 0xe000
	s_nop 0
	global_load_lds_dwordx4 v[194:195], off
	s_cmp_lg_u32 s69, 0
	s_cbranch_scc0 .Lqx26
	s_waitcnt vmcnt(8)
.Lre26:
	s_waitcnt lgkmcnt(0)
	s_barrier
	s_setprio 1
	s_waitcnt lgkmcnt(0)
	v_mfma_f32_16x16x32_bf16 v[118:121], v[122:125], v[162:165], v[118:121]
	v_mfma_f32_16x16x32_bf16 v[114:117], v[134:137], v[162:165], v[114:117]
	v_mfma_f32_16x16x32_bf16 v[102:105], v[122:125], v[190:193], v[102:105]
	v_mfma_f32_16x16x32_bf16 v[98:101], v[134:137], v[190:193], v[98:101]
	v_mfma_f32_16x16x32_bf16 v[86:89], v[122:125], v[206:209], v[86:89]
	v_mfma_f32_16x16x32_bf16 v[82:85], v[134:137], v[206:209], v[82:85]
	v_mfma_f32_16x16x32_bf16 v[70:73], v[122:125], v[214:217], v[70:73]
	v_mfma_f32_16x16x32_bf16 v[66:69], v[134:137], v[214:217], v[66:69]
	v_mfma_f32_16x16x32_bf16 v[118:121], v[126:129], v[166:169], v[118:121]
	v_mfma_f32_16x16x32_bf16 v[114:117], v[138:141], v[166:169], v[114:117]
	v_mfma_f32_16x16x32_bf16 v[102:105], v[126:129], v[202:205], v[102:105]
	v_mfma_f32_16x16x32_bf16 v[98:101], v[138:141], v[202:205], v[98:101]
	v_mfma_f32_16x16x32_bf16 v[86:89], v[126:129], v[210:213], v[86:89]
	v_mfma_f32_16x16x32_bf16 v[82:85], v[138:141], v[210:213], v[82:85]
	v_mfma_f32_16x16x32_bf16 v[70:73], v[126:129], v[218:221], v[70:73]
	v_mfma_f32_16x16x32_bf16 v[66:69], v[138:141], v[218:221], v[66:69]
	s_setprio 0
	s_setprio 1
	v_mfma_f32_16x16x32_bf16 v[158:161], v[142:145], v[162:165], v[158:161]
	v_mfma_f32_16x16x32_bf16 v[130:133], v[150:153], v[162:165], v[130:133]
	v_mfma_f32_16x16x32_bf16 v[110:113], v[142:145], v[190:193], v[110:113]
	v_mfma_f32_16x16x32_bf16 v[106:109], v[150:153], v[190:193], v[106:109]
	v_mfma_f32_16x16x32_bf16 v[94:97], v[142:145], v[206:209], v[94:97]
	v_mfma_f32_16x16x32_bf16 v[90:93], v[150:153], v[206:209], v[90:93]
	v_mfma_f32_16x16x32_bf16 v[78:81], v[142:145], v[214:217], v[78:81]
	v_mfma_f32_16x16x32_bf16 v[74:77], v[150:153], v[214:217], v[74:77]
	v_mfma_f32_16x16x32_bf16 v[158:161], v[146:149], v[166:169], v[158:161]
	v_mfma_f32_16x16x32_bf16 v[130:133], v[154:157], v[166:169], v[130:133]
	v_mfma_f32_16x16x32_bf16 v[110:113], v[146:149], v[202:205], v[110:113]
	v_mfma_f32_16x16x32_bf16 v[106:109], v[154:157], v[202:205], v[106:109]
	v_mfma_f32_16x16x32_bf16 v[94:97], v[146:149], v[210:213], v[94:97]
	v_mfma_f32_16x16x32_bf16 v[90:93], v[154:157], v[210:213], v[90:93]
	v_mfma_f32_16x16x32_bf16 v[78:81], v[146:149], v[218:221], v[78:81]
	v_mfma_f32_16x16x32_bf16 v[74:77], v[154:157], v[218:221], v[74:77]
	s_setprio 0
	s_barrier
	s_add_i32 s0, s61, s34
	v_lshl_add_u64 v[194:195], s[46:47], 0, v[176:177]
	s_mov_b32 m0, s0
	ds_read_b128 v[162:165], v199 offset:16384
	ds_read_b128 v[166:169], v199 offset:17408
	ds_read_b128 v[190:193], v199 offset:18432
	ds_read_b128 v[202:205], v199 offset:19456
	ds_read_b128 v[206:209], v199 offset:20480
	ds_read_b128 v[210:213], v199 offset:21504
	ds_read_b128 v[214:217], v199 offset:22528
	ds_read_b128 v[218:221], v199 offset:23552
	global_load_lds_dwordx4 v[194:195], off
	s_add_i32 m0, s0, 0x2000
	s_add_u32 s0, s46, 0x40000
	v_lshl_add_u64 v[222:223], s[46:47], 0, v[172:173]
	s_addc_u32 s1, s47, 0
	s_add_i32 s70, s62, s34
	global_load_lds_dwordx4 v[222:223], off
	v_lshl_add_u64 v[224:225], s[0:1], 0, v[176:177]
	s_mov_b32 m0, s70
	v_lshl_add_u64 v[226:227], s[48:49], 0, v[174:175]
	global_load_lds_dwordx4 v[224:225], off
	v_lshl_add_u64 v[224:225], s[0:1], 0, v[172:173]
	s_add_i32 m0, s70, 0x2000
	s_nop 0
	global_load_lds_dwordx4 v[224:225], off
	v_lshl_add_u64 v[224:225], s[48:49], 0, v[178:179]
	s_mov_b32 m0, s45
	s_nop 0
	global_load_lds_dwordx4 v[224:225], off
	s_mov_b32 m0, s50
	s_nop 0
	global_load_lds_dwordx4 v[226:227], off
	s_cmp_lg_u32 s69, 0
	s_cbranch_scc0 .Lqx27
	s_waitcnt vmcnt(8)

.Lqx27:
	s_cmp_eq_u32 s41, 0
	s_cbranch_scc1 .Lqy27
	s_waitcnt vmcnt(24)
	s_branch .Lre27

; #define PG8_STAGE(bufoff, gbase, voff) do { _Pragma("unroll") for (int _i = 0; _i < 2; ++_i) \
;         __builtin_amdgcn_global_load_lds((const unsigned*)((const char*)(gbase) + (voff)[_i]), (LAS unsigned*)(lds + (bufoff) + ldsw + _i * 8192), 16, 0, 0); } while (0)
; #define PG8_LDA(dst, b, h) do { _Pragma("unroll") for (int m = 0; m < 4; ++m) _Pragma("unroll") for (int k = 0; k < 2; ++k) dst[m][k] = *(const LAS bf16x8*)(lds + PG8_SA(b, h) + aoff + m * 2048 + k * 1024); } while (0)
; #define PG8_LDB(dst, b, h) do { _Pragma("unroll") for (int n = 0; n < 2; ++n) _Pragma("unroll") for (int k = 0; k < 2; ++k) dst[n][k] = *(const LAS bf16x8*)(lds + PG8_SB(b, h) + boff + n * 2048 + k * 1024); } while (0)
; #define PG8_MMA(ai, bj, At, Bt) do { __builtin_amdgcn_s_setprio(1); _Pragma("unroll") for (int m = 0; m < 4; ++m) _Pragma("unroll") for (int n = 0; n < 2; ++n) _Pragma("unroll") for (int k = 0; k < 2; ++k) \
;         acc[ai][bj][m][n] = __builtin_amdgcn_mfma_f32_16x16x32_bf16(Bt[n][k], At[m][k], acc[ai][bj][m][n], 0, 0, 0); __builtin_amdgcn_s_setprio(0); } while (0)
; #define PG8_WAIT_L(n) asm volatile("s_waitcnt lgkmcnt(" #n ")" ::: "memory")
; #define PG8_BAR __builtin_amdgcn_s_barrier()
; #define PG8_FLAG(v) do { } while (0)
; #define PG8_SCHED __builtin_amdgcn_sched_barrier(0)
; template <class Epi, class Sched, bool APERM, bool ABLK = false, bool RELAX = true>
; __device__ __forceinline__ void gemm_phase(LAS unsigned char* lds, const Gemm g, const Sched& S, const Epi& E) {
;     ...
;             const bool last = (t == nt - 2);
;             const char* a1 = cA + (size_t)(t + 1) * kstepA;
;             const char* a2 = last ? nA : cA + (size_t)(t + 2) * kstepA; const char* b2 = last ? nB : cB + (size_t)(t + 2) * kstep;
;             const char* a3 = a2 + kstepA; const char* b3 = b2 + kstep;
;             PG8_LDB(B0, 0, 0); PG8_LDB(B1, 0, 1); PG8_SCHED; PG8_LDA(At, 0, 0); PG8_STAGE(PG8_SA(1, 1), a1 + hstepA, voffA);
;             PG8_WAIT_V8R; PG8_WAIT_L(0); PG8_BAR; PG8_MMA(0, 0, At, B0); PG8_MMA(0, 1, At, B1); PG8_BAR; PG8_SCHED;
;             PG8_LDA(At, 0, 1); PG8_STAGE(PG8_SB(0, 0), b2, voffB); PG8_STAGE(PG8_SB(0, 1), b2 + hstepB, voffB); PG8_STAGE(PG8_SA(0, 0), a2, voffA);
;             PG8_WAIT_V8R; PG8_FLAG(0u); PG8_WAIT_L(0); PG8_BAR; PG8_MMA(1, 0, At, B0); PG8_MMA(1, 1, At, B1); PG8_BAR; PG8_SCHED;
.LBB0_2338:
	ds_read_b128 v[134:137], v178
	ds_read_b128 v[154:157], v178 offset:1024
	ds_read_b128 v[158:161], v178 offset:2048
	ds_read_b128 v[162:165], v178 offset:3072
	ds_read_b128 v[166:169], v179
	ds_read_b128 v[170:173], v179 offset:1024
	ds_read_b128 v[182:185], v179 offset:2048
	ds_read_b128 v[186:189], v179 offset:3072
	s_add_i32 s60, s60, 2
	s_add_u32 s22, s20, s4
	s_addc_u32 s23, s21, s5
	s_add_u32 s22, s22, 0x900000
	s_addc_u32 s23, s23, 0
	s_cmp_eq_u32 s4, 0xbd00000
	s_cselect_b32 s38, s57, s22
	s_cselect_b32 s39, s13, s23
	s_cselect_b32 s36, s14, s58
	s_cselect_b32 s37, s15, s59
	s_add_u32 s22, s38, 0x480000
	s_addc_u32 s23, s39, 0
	v_lshl_add_u64 v[174:175], v[130:131], 0, s[4:5]
	s_add_i32 m0, s35, 0xc000
	ds_read_b128 v[190:193], v180
	ds_read_b128 v[194:197], v180 offset:1024
	ds_read_b128 v[198:201], v180 offset:2048
	ds_read_b128 v[202:205], v180 offset:3072
	ds_read_b128 v[206:209], v180 offset:4096
	ds_read_b128 v[210:213], v180 offset:5120
	ds_read_b128 v[214:217], v180 offset:6144
	ds_read_b128 v[218:221], v180 offset:7168
	global_load_lds_dwordx4 v[174:175], off
	v_lshl_add_u64 v[174:175], v[132:133], 0, s[4:5]
	s_add_i32 m0, s35, 0xe000
	s_nop 0
	global_load_lds_dwordx4 v[174:175], off
	s_cmp_lg_u32 s60, 0
	s_cbranch_scc0 .Lqx28
	s_waitcnt vmcnt(8)
.Lre28:
	s_waitcnt lgkmcnt(0)
	s_barrier
	s_setprio 1
	s_waitcnt lgkmcnt(0)
	v_mfma_f32_16x16x32_bf16 v[126:129], v[134:137], v[190:193], v[126:129]
	v_mfma_f32_16x16x32_bf16 v[122:125], v[158:161], v[190:193], v[122:125]
	v_mfma_f32_16x16x32_bf16 v[118:121], v[134:137], v[198:201], v[118:121]
	v_mfma_f32_16x16x32_bf16 v[114:117], v[158:161], v[198:201], v[114:117]
	v_mfma_f32_16x16x32_bf16 v[110:113], v[134:137], v[206:209], v[110:113]
	v_mfma_f32_16x16x32_bf16 v[106:109], v[158:161], v[206:209], v[106:109]
	v_mfma_f32_16x16x32_bf16 v[102:105], v[134:137], v[214:217], v[102:105]
	v_mfma_f32_16x16x32_bf16 v[98:101], v[158:161], v[214:217], v[98:101]
	v_mfma_f32_16x16x32_bf16 v[126:129], v[154:157], v[194:197], v[126:129]
	v_mfma_f32_16x16x32_bf16 v[122:125], v[162:165], v[194:197], v[122:125]
	v_mfma_f32_16x16x32_bf16 v[118:121], v[154:157], v[202:205], v[118:121]
	v_mfma_f32_16x16x32_bf16 v[114:117], v[162:165], v[202:205], v[114:117]
	v_mfma_f32_16x16x32_bf16 v[110:113], v[154:157], v[210:213], v[110:113]
	v_mfma_f32_16x16x32_bf16 v[106:109], v[162:165], v[210:213], v[106:109]
	v_mfma_f32_16x16x32_bf16 v[102:105], v[154:157], v[218:221], v[102:105]
	v_mfma_f32_16x16x32_bf16 v[98:101], v[162:165], v[218:221], v[98:101]
	s_setprio 0
	s_setprio 1
	v_mfma_f32_16x16x32_bf16 v[66:69], v[166:169], v[190:193], v[66:69]
	v_mfma_f32_16x16x32_bf16 v[58:61], v[182:185], v[190:193], v[58:61]
	v_mfma_f32_16x16x32_bf16 v[54:57], v[166:169], v[198:201], v[54:57]
	v_mfma_f32_16x16x32_bf16 v[50:53], v[182:185], v[198:201], v[50:53]
	v_mfma_f32_16x16x32_bf16 v[46:49], v[166:169], v[206:209], v[46:49]
	v_mfma_f32_16x16x32_bf16 v[42:45], v[182:185], v[206:209], v[42:45]
	v_mfma_f32_16x16x32_bf16 v[38:41], v[166:169], v[214:217], v[38:41]
	v_mfma_f32_16x16x32_bf16 v[34:37], v[182:185], v[214:217], v[34:37]
	v_mfma_f32_16x16x32_bf16 v[66:69], v[170:173], v[194:197], v[66:69]
	v_mfma_f32_16x16x32_bf16 v[58:61], v[186:189], v[194:197], v[58:61]
	v_mfma_f32_16x16x32_bf16 v[54:57], v[170:173], v[202:205], v[54:57]
	v_mfma_f32_16x16x32_bf16 v[50:53], v[186:189], v[202:205], v[50:53]
	v_mfma_f32_16x16x32_bf16 v[46:49], v[170:173], v[210:213], v[46:49]
	v_mfma_f32_16x16x32_bf16 v[42:45], v[186:189], v[210:213], v[42:45]
	v_mfma_f32_16x16x32_bf16 v[38:41], v[170:173], v[218:221], v[38:41]
	v_mfma_f32_16x16x32_bf16 v[34:37], v[186:189], v[218:221], v[34:37]
	s_setprio 0
	s_barrier
	s_add_i32 s61, s52, s34
	v_lshl_add_u64 v[174:175], s[36:37], 0, v[140:141]
	s_mov_b32 m0, s61
	ds_read_b128 v[190:193], v180 offset:16384
	ds_read_b128 v[194:197], v180 offset:17408
	ds_read_b128 v[198:201], v180 offset:18432
	ds_read_b128 v[202:205], v180 offset:19456
	ds_read_b128 v[206:209], v180 offset:20480
	ds_read_b128 v[210:213], v180 offset:21504
	ds_read_b128 v[214:217], v180 offset:22528
	ds_read_b128 v[218:221], v180 offset:23552
	global_load_lds_dwordx4 v[174:175], off
	s_add_i32 m0, s61, 0x2000
	s_add_u32 s62, s36, 0xb0000
	v_lshl_add_u64 v[222:223], s[36:37], 0, v[144:145]
	s_addc_u32 s63, s37, 0
	s_add_i32 s61, s53, s34
	global_load_lds_dwordx4 v[222:223], off
	v_lshl_add_u64 v[224:225], s[62:63], 0, v[140:141]
	s_mov_b32 m0, s61
	s_nop 0
	global_load_lds_dwordx4 v[224:225], off
	v_lshl_add_u64 v[224:225], s[62:63], 0, v[144:145]
	s_add_i32 m0, s61, 0x2000
	s_nop 0
	global_load_lds_dwordx4 v[224:225], off
	v_lshl_add_u64 v[224:225], s[38:39], 0, v[138:139]
	s_mov_b32 m0, s35
	s_nop 0
	global_load_lds_dwordx4 v[224:225], off
	v_lshl_add_u64 v[224:225], s[38:39], 0, v[142:143]
	s_mov_b32 m0, s40
	s_nop 0
	global_load_lds_dwordx4 v[224:225], off
	s_cmp_lg_u32 s60, 0
	s_cbranch_scc0 .Lqx29
	s_waitcnt vmcnt(8)
